# v13 plus: last 2 LDS-DMA pieces of each 6-piece load segment issued inside the MFMA block (wait 8->6), mid-block setprio flips and redundant lgkmcnt waits removed
# baseline (speedup 1.0000x reference)
.LBB0_252:
	ds_read_b128 v[156:159], v149
	ds_read_b128 v[160:163], v149 offset:1024
	ds_read_b128 v[164:167], v149 offset:2048
	ds_read_b128 v[168:171], v149 offset:3072
	ds_read_b128 v[172:175], v150
	ds_read_b128 v[176:179], v150 offset:1024
	ds_read_b128 v[180:183], v150 offset:2048
	ds_read_b128 v[184:187], v150 offset:3072
	s_add_u32 s26, s24, 0xfffc0080
	s_addc_u32 s27, s25, -1
	s_cmp_eq_u32 s57, 12
	s_cselect_b32 s29, s19, s27
	s_cselect_b32 s28, s53, s26
	s_cselect_b32 s27, s17, s56
	s_cselect_b32 s26, s54, s55
	v_lshl_add_u64 v[146:147], s[24:25], 0, v[138:139]
	s_add_i32 m0, s38, 0xc000
	ds_read_b128 v[188:191], v151
	ds_read_b128 v[192:195], v151 offset:1024
	ds_read_b128 v[196:199], v151 offset:2048
	ds_read_b128 v[200:203], v151 offset:3072
	ds_read_b128 v[204:207], v151 offset:4096
	ds_read_b128 v[208:211], v151 offset:5120
	ds_read_b128 v[212:215], v151 offset:6144
	ds_read_b128 v[216:219], v151 offset:7168
	global_load_lds_dwordx4 v[146:147], off
	v_lshl_add_u64 v[146:147], s[24:25], 0, v[140:141]
	s_add_i32 m0, s38, 0xe000
	s_nop 0
	global_load_lds_dwordx4 v[146:147], off
	s_waitcnt vmcnt(8)
	s_waitcnt lgkmcnt(0)
	s_barrier
	s_setprio 1
	v_mfma_f32_16x16x32_bf16 v[122:125], v[156:159], v[188:191], v[122:125]
	v_mfma_f32_16x16x32_bf16 v[114:117], v[164:167], v[188:191], v[114:117]
	v_mfma_f32_16x16x32_bf16 v[106:109], v[156:159], v[196:199], v[106:109]
	v_mfma_f32_16x16x32_bf16 v[102:105], v[164:167], v[196:199], v[102:105]
	v_mfma_f32_16x16x32_bf16 v[90:93], v[156:159], v[204:207], v[90:93]
	v_mfma_f32_16x16x32_bf16 v[86:89], v[164:167], v[204:207], v[86:89]
	v_mfma_f32_16x16x32_bf16 v[74:77], v[156:159], v[212:215], v[74:77]
	v_mfma_f32_16x16x32_bf16 v[70:73], v[164:167], v[212:215], v[70:73]
	v_mfma_f32_16x16x32_bf16 v[122:125], v[160:163], v[192:195], v[122:125]
	v_mfma_f32_16x16x32_bf16 v[114:117], v[168:171], v[192:195], v[114:117]
	v_mfma_f32_16x16x32_bf16 v[106:109], v[160:163], v[200:203], v[106:109]
	v_mfma_f32_16x16x32_bf16 v[102:105], v[168:171], v[200:203], v[102:105]
	v_mfma_f32_16x16x32_bf16 v[90:93], v[160:163], v[208:211], v[90:93]
	v_mfma_f32_16x16x32_bf16 v[86:89], v[168:171], v[208:211], v[86:89]
	v_mfma_f32_16x16x32_bf16 v[74:77], v[160:163], v[216:219], v[74:77]
	v_mfma_f32_16x16x32_bf16 v[70:73], v[168:171], v[216:219], v[70:73]
	v_mfma_f32_16x16x32_bf16 v[126:129], v[172:175], v[188:191], v[126:129]
	v_mfma_f32_16x16x32_bf16 v[118:121], v[180:183], v[188:191], v[118:121]
	v_mfma_f32_16x16x32_bf16 v[110:113], v[172:175], v[196:199], v[110:113]
	v_mfma_f32_16x16x32_bf16 v[98:101], v[180:183], v[196:199], v[98:101]
	v_mfma_f32_16x16x32_bf16 v[94:97], v[172:175], v[204:207], v[94:97]
	v_mfma_f32_16x16x32_bf16 v[82:85], v[180:183], v[204:207], v[82:85]
	v_mfma_f32_16x16x32_bf16 v[78:81], v[172:175], v[212:215], v[78:81]
	v_mfma_f32_16x16x32_bf16 v[66:69], v[180:183], v[212:215], v[66:69]
	v_mfma_f32_16x16x32_bf16 v[126:129], v[176:179], v[192:195], v[126:129]
	v_mfma_f32_16x16x32_bf16 v[118:121], v[184:187], v[192:195], v[118:121]
	v_mfma_f32_16x16x32_bf16 v[110:113], v[176:179], v[200:203], v[110:113]
	v_mfma_f32_16x16x32_bf16 v[98:101], v[184:187], v[200:203], v[98:101]
	v_mfma_f32_16x16x32_bf16 v[94:97], v[176:179], v[208:211], v[94:97]
	v_mfma_f32_16x16x32_bf16 v[82:85], v[184:187], v[208:211], v[82:85]
	v_mfma_f32_16x16x32_bf16 v[78:81], v[176:179], v[216:219], v[78:81]
	v_mfma_f32_16x16x32_bf16 v[66:69], v[184:187], v[216:219], v[66:69]
	s_setprio 0
	s_barrier
	s_add_i32 s58, s47, s35
	v_lshl_add_u64 v[146:147], s[26:27], 0, v[134:135]
	s_mov_b32 m0, s58
	ds_read_b128 v[188:191], v151 offset:16384
	ds_read_b128 v[192:195], v151 offset:17408
	ds_read_b128 v[196:199], v151 offset:18432
	ds_read_b128 v[200:203], v151 offset:19456
	ds_read_b128 v[204:207], v151 offset:20480
	ds_read_b128 v[208:211], v151 offset:21504
	ds_read_b128 v[212:215], v151 offset:22528
	ds_read_b128 v[216:219], v151 offset:23552
	global_load_lds_dwordx4 v[146:147], off
	s_add_i32 m0, s58, 0x2000
	s_add_u32 s58, s26, 0x40000
	v_lshl_add_u64 v[220:221], s[26:27], 0, v[130:131]
	s_addc_u32 s59, s27, 0
	s_add_i32 s60, s48, s35
	global_load_lds_dwordx4 v[220:221], off
	v_lshl_add_u64 v[222:223], s[58:59], 0, v[134:135]
	s_mov_b32 m0, s60
	v_lshl_add_u64 v[224:225], s[28:29], 0, v[132:133]
	global_load_lds_dwordx4 v[222:223], off
	v_lshl_add_u64 v[222:223], s[58:59], 0, v[130:131]
	s_add_i32 m0, s60, 0x2000
	s_nop 0
	global_load_lds_dwordx4 v[222:223], off
	s_waitcnt vmcnt(6)
	s_waitcnt lgkmcnt(0)
	s_barrier
	s_setprio 1
	v_mfma_f32_16x16x32_bf16 v[58:61], v[156:159], v[188:191], v[58:61]
	v_mfma_f32_16x16x32_bf16 v[54:57], v[164:167], v[188:191], v[54:57]
	v_mfma_f32_16x16x32_bf16 v[42:45], v[156:159], v[196:199], v[42:45]
	v_mfma_f32_16x16x32_bf16 v[38:41], v[164:167], v[196:199], v[38:41]
	v_lshl_add_u64 v[222:223], s[28:29], 0, v[136:137]
	s_mov_b32 m0, s38
	s_nop 0
	global_load_lds_dwordx4 v[222:223], off
	v_mfma_f32_16x16x32_bf16 v[26:29], v[156:159], v[204:207], v[26:29]
	v_mfma_f32_16x16x32_bf16 v[22:25], v[164:167], v[204:207], v[22:25]
	v_mfma_f32_16x16x32_bf16 v[14:17], v[156:159], v[212:215], v[14:17]
	v_mfma_f32_16x16x32_bf16 v[6:9], v[164:167], v[212:215], v[6:9]
	v_mfma_f32_16x16x32_bf16 v[58:61], v[160:163], v[192:195], v[58:61]
	v_mfma_f32_16x16x32_bf16 v[54:57], v[168:171], v[192:195], v[54:57]
	v_mfma_f32_16x16x32_bf16 v[42:45], v[160:163], v[200:203], v[42:45]
	v_mfma_f32_16x16x32_bf16 v[38:41], v[168:171], v[200:203], v[38:41]
	s_mov_b32 m0, s39
	s_nop 0
	global_load_lds_dwordx4 v[224:225], off
	v_mfma_f32_16x16x32_bf16 v[26:29], v[160:163], v[208:211], v[26:29]
	v_mfma_f32_16x16x32_bf16 v[22:25], v[168:171], v[208:211], v[22:25]
	v_mfma_f32_16x16x32_bf16 v[14:17], v[160:163], v[216:219], v[14:17]
	v_mfma_f32_16x16x32_bf16 v[6:9], v[168:171], v[216:219], v[6:9]
	v_mfma_f32_16x16x32_bf16 v[62:65], v[172:175], v[188:191], v[62:65]
	v_mfma_f32_16x16x32_bf16 v[50:53], v[180:183], v[188:191], v[50:53]
	v_mfma_f32_16x16x32_bf16 v[46:49], v[172:175], v[196:199], v[46:49]
	v_mfma_f32_16x16x32_bf16 v[34:37], v[180:183], v[196:199], v[34:37]
	v_mfma_f32_16x16x32_bf16 v[30:33], v[172:175], v[204:207], v[30:33]
	v_mfma_f32_16x16x32_bf16 v[18:21], v[180:183], v[204:207], v[18:21]
	v_mfma_f32_16x16x32_bf16 v[10:13], v[172:175], v[212:215], v[10:13]
	v_mfma_f32_16x16x32_bf16 v[2:5], v[180:183], v[212:215], v[2:5]
	v_mfma_f32_16x16x32_bf16 v[62:65], v[176:179], v[192:195], v[62:65]
	v_mfma_f32_16x16x32_bf16 v[50:53], v[184:187], v[192:195], v[50:53]
	v_mfma_f32_16x16x32_bf16 v[46:49], v[176:179], v[200:203], v[46:49]
	v_mfma_f32_16x16x32_bf16 v[34:37], v[184:187], v[200:203], v[34:37]
	v_mfma_f32_16x16x32_bf16 v[30:33], v[176:179], v[208:211], v[30:33]
	v_mfma_f32_16x16x32_bf16 v[18:21], v[184:187], v[208:211], v[18:21]
	v_mfma_f32_16x16x32_bf16 v[10:13], v[176:179], v[216:219], v[10:13]
	v_mfma_f32_16x16x32_bf16 v[2:5], v[184:187], v[216:219], v[2:5]
	s_setprio 0
	s_barrier
	ds_read_b128 v[156:159], v154
	ds_read_b128 v[160:163], v154 offset:1024
	ds_read_b128 v[164:167], v154 offset:2048
	ds_read_b128 v[168:171], v154 offset:3072
	ds_read_b128 v[172:175], v155
	ds_read_b128 v[176:179], v155 offset:1024
	ds_read_b128 v[180:183], v155 offset:2048
	ds_read_b128 v[184:187], v155 offset:3072
	s_add_u32 s28, s28, 0x40000
	s_addc_u32 s29, s29, 0
	s_mov_b32 m0, s40
	v_lshl_add_u64 v[226:227], s[28:29], 0, v[136:137]
	ds_read_b128 v[188:191], v151 offset:32768
	ds_read_b128 v[192:195], v151 offset:33792
	ds_read_b128 v[196:199], v151 offset:34816
	ds_read_b128 v[200:203], v151 offset:35840
	ds_read_b128 v[204:207], v151 offset:36864
	ds_read_b128 v[208:211], v151 offset:37888
	ds_read_b128 v[212:215], v151 offset:38912
	ds_read_b128 v[216:219], v151 offset:39936
	global_load_lds_dwordx4 v[226:227], off
	v_lshl_add_u64 v[226:227], s[28:29], 0, v[132:133]
	s_mov_b32 m0, s41
	s_nop 0
	global_load_lds_dwordx4 v[226:227], off
	s_waitcnt vmcnt(8)
	s_waitcnt lgkmcnt(0)
	s_barrier
	s_setprio 1
	v_mfma_f32_16x16x32_bf16 v[122:125], v[156:159], v[188:191], v[122:125]
	v_mfma_f32_16x16x32_bf16 v[114:117], v[164:167], v[188:191], v[114:117]
	v_mfma_f32_16x16x32_bf16 v[106:109], v[156:159], v[196:199], v[106:109]
	v_mfma_f32_16x16x32_bf16 v[102:105], v[164:167], v[196:199], v[102:105]
	v_mfma_f32_16x16x32_bf16 v[90:93], v[156:159], v[204:207], v[90:93]
	v_mfma_f32_16x16x32_bf16 v[86:89], v[164:167], v[204:207], v[86:89]
	v_mfma_f32_16x16x32_bf16 v[74:77], v[156:159], v[212:215], v[74:77]
	v_mfma_f32_16x16x32_bf16 v[70:73], v[164:167], v[212:215], v[70:73]
	v_mfma_f32_16x16x32_bf16 v[122:125], v[160:163], v[192:195], v[122:125]
	v_mfma_f32_16x16x32_bf16 v[114:117], v[168:171], v[192:195], v[114:117]
	v_mfma_f32_16x16x32_bf16 v[106:109], v[160:163], v[200:203], v[106:109]
	v_mfma_f32_16x16x32_bf16 v[102:105], v[168:171], v[200:203], v[102:105]
	v_mfma_f32_16x16x32_bf16 v[90:93], v[160:163], v[208:211], v[90:93]
	v_mfma_f32_16x16x32_bf16 v[86:89], v[168:171], v[208:211], v[86:89]
	v_mfma_f32_16x16x32_bf16 v[74:77], v[160:163], v[216:219], v[74:77]
	v_mfma_f32_16x16x32_bf16 v[70:73], v[168:171], v[216:219], v[70:73]
	v_mfma_f32_16x16x32_bf16 v[126:129], v[172:175], v[188:191], v[126:129]
	v_mfma_f32_16x16x32_bf16 v[118:121], v[180:183], v[188:191], v[118:121]
	v_mfma_f32_16x16x32_bf16 v[110:113], v[172:175], v[196:199], v[110:113]
	v_mfma_f32_16x16x32_bf16 v[98:101], v[180:183], v[196:199], v[98:101]
	v_mfma_f32_16x16x32_bf16 v[94:97], v[172:175], v[204:207], v[94:97]
	v_mfma_f32_16x16x32_bf16 v[82:85], v[180:183], v[204:207], v[82:85]
	v_mfma_f32_16x16x32_bf16 v[78:81], v[172:175], v[212:215], v[78:81]
	v_mfma_f32_16x16x32_bf16 v[66:69], v[180:183], v[212:215], v[66:69]
	v_mfma_f32_16x16x32_bf16 v[126:129], v[176:179], v[192:195], v[126:129]
	v_mfma_f32_16x16x32_bf16 v[118:121], v[184:187], v[192:195], v[118:121]
	v_mfma_f32_16x16x32_bf16 v[110:113], v[176:179], v[200:203], v[110:113]
	v_mfma_f32_16x16x32_bf16 v[98:101], v[184:187], v[200:203], v[98:101]
	v_mfma_f32_16x16x32_bf16 v[94:97], v[176:179], v[208:211], v[94:97]
	v_mfma_f32_16x16x32_bf16 v[82:85], v[184:187], v[208:211], v[82:85]
	v_mfma_f32_16x16x32_bf16 v[78:81], v[176:179], v[216:219], v[78:81]
	v_mfma_f32_16x16x32_bf16 v[66:69], v[184:187], v[216:219], v[66:69]
	s_setprio 0
	s_barrier
	s_add_i32 s28, s51, s35
	v_lshl_add_u64 v[146:147], v[146:147], 0, s[12:13]
	s_mov_b32 m0, s28
	ds_read_b128 v[188:191], v151 offset:49152
	ds_read_b128 v[192:195], v151 offset:50176
	ds_read_b128 v[196:199], v151 offset:51200
	ds_read_b128 v[200:203], v151 offset:52224
	ds_read_b128 v[204:207], v151 offset:53248
	ds_read_b128 v[208:211], v151 offset:54272
	ds_read_b128 v[212:215], v151 offset:55296
	ds_read_b128 v[216:219], v151 offset:56320
	global_load_lds_dwordx4 v[146:147], off
	s_add_i32 m0, s28, 0x2000
	s_add_u32 s26, s26, 0x40080
	v_lshl_add_u64 v[146:147], v[220:221], 0, s[12:13]
	s_addc_u32 s27, s27, 0
	s_add_i32 s28, s52, s35
	global_load_lds_dwordx4 v[146:147], off
	v_lshl_add_u64 v[146:147], s[26:27], 0, v[134:135]
	s_mov_b32 m0, s28
	s_nop 0
	global_load_lds_dwordx4 v[146:147], off
	v_lshl_add_u64 v[146:147], s[26:27], 0, v[130:131]
	s_add_i32 m0, s28, 0x2000
	s_nop 0
	global_load_lds_dwordx4 v[146:147], off
	s_waitcnt vmcnt(6)
	s_waitcnt lgkmcnt(0)
	s_barrier
	s_setprio 1
	v_mfma_f32_16x16x32_bf16 v[58:61], v[156:159], v[188:191], v[58:61]
	v_mfma_f32_16x16x32_bf16 v[54:57], v[164:167], v[188:191], v[54:57]
	v_mfma_f32_16x16x32_bf16 v[42:45], v[156:159], v[196:199], v[42:45]
	v_mfma_f32_16x16x32_bf16 v[38:41], v[164:167], v[196:199], v[38:41]
	v_lshl_add_u64 v[146:147], v[222:223], 0, s[12:13]
	s_mov_b32 m0, s44
	s_nop 0
	global_load_lds_dwordx4 v[146:147], off
	v_mfma_f32_16x16x32_bf16 v[26:29], v[156:159], v[204:207], v[26:29]
	v_mfma_f32_16x16x32_bf16 v[22:25], v[164:167], v[204:207], v[22:25]
	v_mfma_f32_16x16x32_bf16 v[14:17], v[156:159], v[212:215], v[14:17]
	v_mfma_f32_16x16x32_bf16 v[6:9], v[164:167], v[212:215], v[6:9]
	v_mfma_f32_16x16x32_bf16 v[58:61], v[160:163], v[192:195], v[58:61]
	v_mfma_f32_16x16x32_bf16 v[54:57], v[168:171], v[192:195], v[54:57]
	v_mfma_f32_16x16x32_bf16 v[42:45], v[160:163], v[200:203], v[42:45]
	v_mfma_f32_16x16x32_bf16 v[38:41], v[168:171], v[200:203], v[38:41]
	v_lshl_add_u64 v[146:147], v[224:225], 0, s[12:13]
	s_mov_b32 m0, s45
	s_nop 0
	global_load_lds_dwordx4 v[146:147], off
	v_mfma_f32_16x16x32_bf16 v[26:29], v[160:163], v[208:211], v[26:29]
	v_mfma_f32_16x16x32_bf16 v[22:25], v[168:171], v[208:211], v[22:25]
	v_mfma_f32_16x16x32_bf16 v[14:17], v[160:163], v[216:219], v[14:17]
	v_mfma_f32_16x16x32_bf16 v[6:9], v[168:171], v[216:219], v[6:9]
	v_mfma_f32_16x16x32_bf16 v[62:65], v[172:175], v[188:191], v[62:65]
	v_mfma_f32_16x16x32_bf16 v[50:53], v[180:183], v[188:191], v[50:53]
	v_mfma_f32_16x16x32_bf16 v[46:49], v[172:175], v[196:199], v[46:49]
	v_mfma_f32_16x16x32_bf16 v[34:37], v[180:183], v[196:199], v[34:37]
	v_mfma_f32_16x16x32_bf16 v[30:33], v[172:175], v[204:207], v[30:33]
	v_mfma_f32_16x16x32_bf16 v[18:21], v[180:183], v[204:207], v[18:21]
	v_mfma_f32_16x16x32_bf16 v[10:13], v[172:175], v[212:215], v[10:13]
	v_mfma_f32_16x16x32_bf16 v[2:5], v[180:183], v[212:215], v[2:5]
	v_mfma_f32_16x16x32_bf16 v[62:65], v[176:179], v[192:195], v[62:65]
	v_mfma_f32_16x16x32_bf16 v[50:53], v[184:187], v[192:195], v[50:53]
	v_mfma_f32_16x16x32_bf16 v[46:49], v[176:179], v[200:203], v[46:49]
	v_mfma_f32_16x16x32_bf16 v[34:37], v[184:187], v[200:203], v[34:37]
	v_mfma_f32_16x16x32_bf16 v[30:33], v[176:179], v[208:211], v[30:33]
	v_mfma_f32_16x16x32_bf16 v[18:21], v[184:187], v[208:211], v[18:21]
	v_mfma_f32_16x16x32_bf16 v[10:13], v[176:179], v[216:219], v[10:13]
	v_mfma_f32_16x16x32_bf16 v[2:5], v[184:187], v[216:219], v[2:5]
	s_setprio 0
	s_barrier
	s_add_i32 s57, s57, 2
	s_add_u32 s24, s24, 0x100
	s_addc_u32 s25, s25, 0
	s_add_u32 s55, s55, 0x100
	s_addc_u32 s56, s56, 0
	s_cmp_gt_u32 s57, 13
	s_cbranch_scc0 .LBB0_252
	s_and_b64 vcc, exec, s[14:15]
	s_cbranch_vccz .LBB0_255
	s_barrier

.LBB0_294:
	ds_read_b128 v[130:133], v207
	ds_read_b128 v[134:137], v207 offset:1024
	ds_read_b128 v[138:141], v207 offset:2048
	ds_read_b128 v[142:145], v207 offset:3072
	ds_read_b128 v[146:149], v208
	ds_read_b128 v[150:153], v208 offset:1024
	ds_read_b128 v[154:157], v208 offset:2048
	ds_read_b128 v[158:161], v208 offset:3072
	s_add_u32 s20, s18, 0xfff50080
	s_addc_u32 s21, s19, -1
	s_cmp_eq_u32 s51, 40
	s_cselect_b32 s23, s9, s21
	s_cselect_b32 s22, s8, s20
	s_cselect_b32 s21, s11, s50
	s_cselect_b32 s20, s10, s49
	v_lshl_add_u64 v[218:219], s[18:19], 0, v[186:187]
	s_add_i32 m0, s31, 0xc000
	ds_read_b128 v[162:165], v209
	ds_read_b128 v[166:169], v209 offset:1024
	ds_read_b128 v[170:173], v209 offset:2048
	ds_read_b128 v[174:177], v209 offset:3072
	ds_read_b128 v[194:197], v209 offset:4096
	ds_read_b128 v[198:201], v209 offset:5120
	ds_read_b128 v[202:205], v209 offset:6144
	ds_read_b128 v[214:217], v209 offset:7168
	global_load_lds_dwordx4 v[218:219], off
	v_lshl_add_u64 v[218:219], s[18:19], 0, v[188:189]
	s_add_i32 m0, s31, 0xe000
	s_nop 0
	global_load_lds_dwordx4 v[218:219], off
	s_waitcnt vmcnt(8)
	s_waitcnt lgkmcnt(0)
	s_barrier
	s_setprio 1
	v_mfma_f32_16x16x32_bf16 v[126:129], v[130:133], v[162:165], v[126:129]
	v_mfma_f32_16x16x32_bf16 v[122:125], v[138:141], v[162:165], v[122:125]
	v_mfma_f32_16x16x32_bf16 v[110:113], v[130:133], v[170:173], v[110:113]
	v_mfma_f32_16x16x32_bf16 v[106:109], v[138:141], v[170:173], v[106:109]
	v_mfma_f32_16x16x32_bf16 v[94:97], v[130:133], v[194:197], v[94:97]
	v_mfma_f32_16x16x32_bf16 v[90:93], v[138:141], v[194:197], v[90:93]
	v_mfma_f32_16x16x32_bf16 v[78:81], v[130:133], v[202:205], v[78:81]
	v_mfma_f32_16x16x32_bf16 v[74:77], v[138:141], v[202:205], v[74:77]
	v_mfma_f32_16x16x32_bf16 v[126:129], v[134:137], v[166:169], v[126:129]
	v_mfma_f32_16x16x32_bf16 v[122:125], v[142:145], v[166:169], v[122:125]
	v_mfma_f32_16x16x32_bf16 v[110:113], v[134:137], v[174:177], v[110:113]
	v_mfma_f32_16x16x32_bf16 v[106:109], v[142:145], v[174:177], v[106:109]
	v_mfma_f32_16x16x32_bf16 v[94:97], v[134:137], v[198:201], v[94:97]
	v_mfma_f32_16x16x32_bf16 v[90:93], v[142:145], v[198:201], v[90:93]
	v_mfma_f32_16x16x32_bf16 v[78:81], v[134:137], v[214:217], v[78:81]
	v_mfma_f32_16x16x32_bf16 v[74:77], v[142:145], v[214:217], v[74:77]
	v_mfma_f32_16x16x32_bf16 v[118:121], v[146:149], v[162:165], v[118:121]
	v_mfma_f32_16x16x32_bf16 v[114:117], v[154:157], v[162:165], v[114:117]
	v_mfma_f32_16x16x32_bf16 v[102:105], v[146:149], v[170:173], v[102:105]
	v_mfma_f32_16x16x32_bf16 v[98:101], v[154:157], v[170:173], v[98:101]
	v_mfma_f32_16x16x32_bf16 v[86:89], v[146:149], v[194:197], v[86:89]
	v_mfma_f32_16x16x32_bf16 v[82:85], v[154:157], v[194:197], v[82:85]
	v_mfma_f32_16x16x32_bf16 v[70:73], v[146:149], v[202:205], v[70:73]
	v_mfma_f32_16x16x32_bf16 v[66:69], v[154:157], v[202:205], v[66:69]
	v_mfma_f32_16x16x32_bf16 v[118:121], v[150:153], v[166:169], v[118:121]
	v_mfma_f32_16x16x32_bf16 v[114:117], v[158:161], v[166:169], v[114:117]
	v_mfma_f32_16x16x32_bf16 v[102:105], v[150:153], v[174:177], v[102:105]
	v_mfma_f32_16x16x32_bf16 v[98:101], v[158:161], v[174:177], v[98:101]
	v_mfma_f32_16x16x32_bf16 v[86:89], v[150:153], v[198:201], v[86:89]
	v_mfma_f32_16x16x32_bf16 v[82:85], v[158:161], v[198:201], v[82:85]
	v_mfma_f32_16x16x32_bf16 v[70:73], v[150:153], v[214:217], v[70:73]
	v_mfma_f32_16x16x32_bf16 v[66:69], v[158:161], v[214:217], v[66:69]
	s_setprio 0
	s_barrier
	s_add_i32 s52, s41, s30
	v_lshl_add_u64 v[218:219], s[20:21], 0, v[180:181]
	s_mov_b32 m0, s52
	ds_read_b128 v[162:165], v209 offset:16384
	ds_read_b128 v[166:169], v209 offset:17408
	ds_read_b128 v[170:173], v209 offset:18432
	ds_read_b128 v[174:177], v209 offset:19456
	ds_read_b128 v[194:197], v209 offset:20480
	ds_read_b128 v[198:201], v209 offset:21504
	ds_read_b128 v[202:205], v209 offset:22528
	ds_read_b128 v[214:217], v209 offset:23552
	global_load_lds_dwordx4 v[218:219], off
	s_add_i32 m0, s52, 0x2000
	s_add_u32 s52, s20, 0xb0000
	v_lshl_add_u64 v[220:221], s[20:21], 0, v[184:185]
	s_addc_u32 s53, s21, 0
	s_add_i32 s54, s42, s30
	global_load_lds_dwordx4 v[220:221], off
	v_lshl_add_u64 v[222:223], s[52:53], 0, v[180:181]
	s_mov_b32 m0, s54
	v_lshl_add_u64 v[224:225], s[22:23], 0, v[182:183]
	global_load_lds_dwordx4 v[222:223], off
	v_lshl_add_u64 v[222:223], s[52:53], 0, v[184:185]
	s_add_i32 m0, s54, 0x2000
	s_nop 0
	global_load_lds_dwordx4 v[222:223], off
	s_waitcnt vmcnt(6)
	s_waitcnt lgkmcnt(0)
	s_barrier
	s_setprio 1
	v_mfma_f32_16x16x32_bf16 v[62:65], v[130:133], v[162:165], v[62:65]
	v_mfma_f32_16x16x32_bf16 v[58:61], v[138:141], v[162:165], v[58:61]
	v_mfma_f32_16x16x32_bf16 v[46:49], v[130:133], v[170:173], v[46:49]
	v_mfma_f32_16x16x32_bf16 v[42:45], v[138:141], v[170:173], v[42:45]
	v_lshl_add_u64 v[222:223], s[22:23], 0, v[178:179]
	s_mov_b32 m0, s31
	s_nop 0
	global_load_lds_dwordx4 v[222:223], off
	v_mfma_f32_16x16x32_bf16 v[30:33], v[130:133], v[194:197], v[30:33]
	v_mfma_f32_16x16x32_bf16 v[26:29], v[138:141], v[194:197], v[26:29]
	v_mfma_f32_16x16x32_bf16 v[14:17], v[130:133], v[202:205], v[14:17]
	v_mfma_f32_16x16x32_bf16 v[10:13], v[138:141], v[202:205], v[10:13]
	v_mfma_f32_16x16x32_bf16 v[62:65], v[134:137], v[166:169], v[62:65]
	v_mfma_f32_16x16x32_bf16 v[58:61], v[142:145], v[166:169], v[58:61]
	v_mfma_f32_16x16x32_bf16 v[46:49], v[134:137], v[174:177], v[46:49]
	v_mfma_f32_16x16x32_bf16 v[42:45], v[142:145], v[174:177], v[42:45]
	s_mov_b32 m0, s33
	s_nop 0
	global_load_lds_dwordx4 v[224:225], off
	v_mfma_f32_16x16x32_bf16 v[30:33], v[134:137], v[198:201], v[30:33]
	v_mfma_f32_16x16x32_bf16 v[26:29], v[142:145], v[198:201], v[26:29]
	v_mfma_f32_16x16x32_bf16 v[14:17], v[134:137], v[214:217], v[14:17]
	v_mfma_f32_16x16x32_bf16 v[10:13], v[142:145], v[214:217], v[10:13]
	v_mfma_f32_16x16x32_bf16 v[54:57], v[146:149], v[162:165], v[54:57]
	v_mfma_f32_16x16x32_bf16 v[50:53], v[154:157], v[162:165], v[50:53]
	v_mfma_f32_16x16x32_bf16 v[38:41], v[146:149], v[170:173], v[38:41]
	v_mfma_f32_16x16x32_bf16 v[34:37], v[154:157], v[170:173], v[34:37]
	v_mfma_f32_16x16x32_bf16 v[22:25], v[146:149], v[194:197], v[22:25]
	v_mfma_f32_16x16x32_bf16 v[18:21], v[154:157], v[194:197], v[18:21]
	v_mfma_f32_16x16x32_bf16 v[6:9], v[146:149], v[202:205], v[6:9]
	v_mfma_f32_16x16x32_bf16 v[2:5], v[154:157], v[202:205], v[2:5]
	v_mfma_f32_16x16x32_bf16 v[54:57], v[150:153], v[166:169], v[54:57]
	v_mfma_f32_16x16x32_bf16 v[50:53], v[158:161], v[166:169], v[50:53]
	v_mfma_f32_16x16x32_bf16 v[38:41], v[150:153], v[174:177], v[38:41]
	v_mfma_f32_16x16x32_bf16 v[34:37], v[158:161], v[174:177], v[34:37]
	v_mfma_f32_16x16x32_bf16 v[22:25], v[150:153], v[198:201], v[22:25]
	v_mfma_f32_16x16x32_bf16 v[18:21], v[158:161], v[198:201], v[18:21]
	v_mfma_f32_16x16x32_bf16 v[6:9], v[150:153], v[214:217], v[6:9]
	v_mfma_f32_16x16x32_bf16 v[2:5], v[158:161], v[214:217], v[2:5]
	s_setprio 0
	s_barrier
	ds_read_b128 v[130:133], v211
	ds_read_b128 v[134:137], v211 offset:1024
	ds_read_b128 v[138:141], v211 offset:2048
	ds_read_b128 v[142:145], v211 offset:3072
	ds_read_b128 v[146:149], v212
	ds_read_b128 v[150:153], v212 offset:1024
	ds_read_b128 v[154:157], v212 offset:2048
	ds_read_b128 v[158:161], v212 offset:3072
	s_add_u32 s22, s22, 0xb0000
	s_addc_u32 s23, s23, 0
	s_mov_b32 m0, s34
	v_lshl_add_u64 v[226:227], s[22:23], 0, v[178:179]
	ds_read_b128 v[162:165], v209 offset:32768
	ds_read_b128 v[166:169], v209 offset:33792
	ds_read_b128 v[170:173], v209 offset:34816
	ds_read_b128 v[174:177], v209 offset:35840
	ds_read_b128 v[194:197], v209 offset:36864
	ds_read_b128 v[198:201], v209 offset:37888
	ds_read_b128 v[202:205], v209 offset:38912
	ds_read_b128 v[214:217], v209 offset:39936
	global_load_lds_dwordx4 v[226:227], off
	v_lshl_add_u64 v[226:227], s[22:23], 0, v[182:183]
	s_mov_b32 m0, s35
	s_nop 0
	global_load_lds_dwordx4 v[226:227], off
	s_waitcnt vmcnt(8)
	s_waitcnt lgkmcnt(0)
	s_barrier
	s_setprio 1
	v_mfma_f32_16x16x32_bf16 v[126:129], v[130:133], v[162:165], v[126:129]
	v_mfma_f32_16x16x32_bf16 v[122:125], v[138:141], v[162:165], v[122:125]
	v_mfma_f32_16x16x32_bf16 v[110:113], v[130:133], v[170:173], v[110:113]
	v_mfma_f32_16x16x32_bf16 v[106:109], v[138:141], v[170:173], v[106:109]
	v_mfma_f32_16x16x32_bf16 v[94:97], v[130:133], v[194:197], v[94:97]
	v_mfma_f32_16x16x32_bf16 v[90:93], v[138:141], v[194:197], v[90:93]
	v_mfma_f32_16x16x32_bf16 v[78:81], v[130:133], v[202:205], v[78:81]
	v_mfma_f32_16x16x32_bf16 v[74:77], v[138:141], v[202:205], v[74:77]
	v_mfma_f32_16x16x32_bf16 v[126:129], v[134:137], v[166:169], v[126:129]
	v_mfma_f32_16x16x32_bf16 v[122:125], v[142:145], v[166:169], v[122:125]
	v_mfma_f32_16x16x32_bf16 v[110:113], v[134:137], v[174:177], v[110:113]
	v_mfma_f32_16x16x32_bf16 v[106:109], v[142:145], v[174:177], v[106:109]
	v_mfma_f32_16x16x32_bf16 v[94:97], v[134:137], v[198:201], v[94:97]
	v_mfma_f32_16x16x32_bf16 v[90:93], v[142:145], v[198:201], v[90:93]
	v_mfma_f32_16x16x32_bf16 v[78:81], v[134:137], v[214:217], v[78:81]
	v_mfma_f32_16x16x32_bf16 v[74:77], v[142:145], v[214:217], v[74:77]
	v_mfma_f32_16x16x32_bf16 v[118:121], v[146:149], v[162:165], v[118:121]
	v_mfma_f32_16x16x32_bf16 v[114:117], v[154:157], v[162:165], v[114:117]
	v_mfma_f32_16x16x32_bf16 v[102:105], v[146:149], v[170:173], v[102:105]
	v_mfma_f32_16x16x32_bf16 v[98:101], v[154:157], v[170:173], v[98:101]
	v_mfma_f32_16x16x32_bf16 v[86:89], v[146:149], v[194:197], v[86:89]
	v_mfma_f32_16x16x32_bf16 v[82:85], v[154:157], v[194:197], v[82:85]
	v_mfma_f32_16x16x32_bf16 v[70:73], v[146:149], v[202:205], v[70:73]
	v_mfma_f32_16x16x32_bf16 v[66:69], v[154:157], v[202:205], v[66:69]
	v_mfma_f32_16x16x32_bf16 v[118:121], v[150:153], v[166:169], v[118:121]
	v_mfma_f32_16x16x32_bf16 v[114:117], v[158:161], v[166:169], v[114:117]
	v_mfma_f32_16x16x32_bf16 v[102:105], v[150:153], v[174:177], v[102:105]
	v_mfma_f32_16x16x32_bf16 v[98:101], v[158:161], v[174:177], v[98:101]
	v_mfma_f32_16x16x32_bf16 v[86:89], v[150:153], v[198:201], v[86:89]
	v_mfma_f32_16x16x32_bf16 v[82:85], v[158:161], v[198:201], v[82:85]
	v_mfma_f32_16x16x32_bf16 v[70:73], v[150:153], v[214:217], v[70:73]
	v_mfma_f32_16x16x32_bf16 v[66:69], v[158:161], v[214:217], v[66:69]
	s_setprio 0
	s_barrier
	s_add_i32 s22, s43, s30
	v_lshl_add_u64 v[218:219], v[218:219], 0, s[14:15]
	s_mov_b32 m0, s22
	ds_read_b128 v[162:165], v209 offset:49152
	ds_read_b128 v[166:169], v209 offset:50176
	ds_read_b128 v[170:173], v209 offset:51200
	ds_read_b128 v[174:177], v209 offset:52224
	ds_read_b128 v[194:197], v209 offset:53248
	ds_read_b128 v[198:201], v209 offset:54272
	ds_read_b128 v[202:205], v209 offset:55296
	ds_read_b128 v[214:217], v209 offset:56320
	global_load_lds_dwordx4 v[218:219], off
	s_add_i32 m0, s22, 0x2000
	s_add_u32 s20, s20, 0xb0080
	v_lshl_add_u64 v[218:219], v[220:221], 0, s[14:15]
	s_addc_u32 s21, s21, 0
	s_add_i32 s22, s44, s30
	global_load_lds_dwordx4 v[218:219], off
	v_lshl_add_u64 v[218:219], s[20:21], 0, v[180:181]
	s_mov_b32 m0, s22
	s_nop 0
	global_load_lds_dwordx4 v[218:219], off
	v_lshl_add_u64 v[218:219], s[20:21], 0, v[184:185]
	s_add_i32 m0, s22, 0x2000
	s_nop 0
	global_load_lds_dwordx4 v[218:219], off
	s_waitcnt vmcnt(6)
	s_waitcnt lgkmcnt(0)
	s_barrier
	s_setprio 1
	v_mfma_f32_16x16x32_bf16 v[62:65], v[130:133], v[162:165], v[62:65]
	v_mfma_f32_16x16x32_bf16 v[58:61], v[138:141], v[162:165], v[58:61]
	v_mfma_f32_16x16x32_bf16 v[46:49], v[130:133], v[170:173], v[46:49]
	v_mfma_f32_16x16x32_bf16 v[42:45], v[138:141], v[170:173], v[42:45]
	v_lshl_add_u64 v[218:219], v[222:223], 0, s[14:15]
	s_mov_b32 m0, s37
	s_nop 0
	global_load_lds_dwordx4 v[218:219], off
	v_mfma_f32_16x16x32_bf16 v[30:33], v[130:133], v[194:197], v[30:33]
	v_mfma_f32_16x16x32_bf16 v[26:29], v[138:141], v[194:197], v[26:29]
	v_mfma_f32_16x16x32_bf16 v[14:17], v[130:133], v[202:205], v[14:17]
	v_mfma_f32_16x16x32_bf16 v[10:13], v[138:141], v[202:205], v[10:13]
	v_mfma_f32_16x16x32_bf16 v[62:65], v[134:137], v[166:169], v[62:65]
	v_mfma_f32_16x16x32_bf16 v[58:61], v[142:145], v[166:169], v[58:61]
	v_mfma_f32_16x16x32_bf16 v[46:49], v[134:137], v[174:177], v[46:49]
	v_mfma_f32_16x16x32_bf16 v[42:45], v[142:145], v[174:177], v[42:45]
	v_lshl_add_u64 v[218:219], v[224:225], 0, s[14:15]
	s_mov_b32 m0, s38
	s_nop 0
	global_load_lds_dwordx4 v[218:219], off
	v_mfma_f32_16x16x32_bf16 v[30:33], v[134:137], v[198:201], v[30:33]
	v_mfma_f32_16x16x32_bf16 v[26:29], v[142:145], v[198:201], v[26:29]
	v_mfma_f32_16x16x32_bf16 v[14:17], v[134:137], v[214:217], v[14:17]
	v_mfma_f32_16x16x32_bf16 v[10:13], v[142:145], v[214:217], v[10:13]
	v_mfma_f32_16x16x32_bf16 v[54:57], v[146:149], v[162:165], v[54:57]
	v_mfma_f32_16x16x32_bf16 v[50:53], v[154:157], v[162:165], v[50:53]
	v_mfma_f32_16x16x32_bf16 v[38:41], v[146:149], v[170:173], v[38:41]
	v_mfma_f32_16x16x32_bf16 v[34:37], v[154:157], v[170:173], v[34:37]
	v_mfma_f32_16x16x32_bf16 v[22:25], v[146:149], v[194:197], v[22:25]
	v_mfma_f32_16x16x32_bf16 v[18:21], v[154:157], v[194:197], v[18:21]
	v_mfma_f32_16x16x32_bf16 v[6:9], v[146:149], v[202:205], v[6:9]
	v_mfma_f32_16x16x32_bf16 v[2:5], v[154:157], v[202:205], v[2:5]
	v_mfma_f32_16x16x32_bf16 v[54:57], v[150:153], v[166:169], v[54:57]
	v_mfma_f32_16x16x32_bf16 v[50:53], v[158:161], v[166:169], v[50:53]
	v_mfma_f32_16x16x32_bf16 v[38:41], v[150:153], v[174:177], v[38:41]
	v_mfma_f32_16x16x32_bf16 v[34:37], v[158:161], v[174:177], v[34:37]
	v_mfma_f32_16x16x32_bf16 v[22:25], v[150:153], v[198:201], v[22:25]
	v_mfma_f32_16x16x32_bf16 v[18:21], v[158:161], v[198:201], v[18:21]
	v_mfma_f32_16x16x32_bf16 v[6:9], v[150:153], v[214:217], v[6:9]
	v_mfma_f32_16x16x32_bf16 v[2:5], v[158:161], v[214:217], v[2:5]
	s_setprio 0
	s_barrier
	s_add_i32 s51, s51, 2
	s_add_u32 s18, s18, 0x100
	s_addc_u32 s19, s19, 0
	s_add_u32 s49, s49, 0x100
	s_addc_u32 s50, s50, 0
	s_cmp_gt_u32 s51, 41
	s_cbranch_scc0 .LBB0_294
	s_load_dwordx16 s[80:95], s[76:77], 0x0
	v_lshl_add_u32 v198, s48, 8, v1
	v_lshl_or_b32 v194, s16, 8, v206
	v_ashrrev_i32_e32 v195, 31, v194
	v_ashrrev_i32_e32 v199, 31, v198
	s_waitcnt lgkmcnt(0)
	v_lshl_add_u64 v[196:197], v[194:195], 2, s[80:81]
	v_lshlrev_b64 v[130:131], 12, v[198:199]
	v_lshl_add_u64 v[130:131], v[196:197], 0, v[130:131]
	global_load_dwordx4 v[214:217], v[130:131], off nt
	global_load_dwordx4 v[218:221], v[130:131], off offset:16 nt
	global_load_dwordx4 v[222:225], v[130:131], off offset:512 nt
	global_load_dwordx4 v[226:229], v[130:131], off offset:528 nt
	v_or_b32_e32 v204, 16, v198
	v_or_b32_e32 v202, 32, v198
	v_or_b32_e32 v200, 48, v198
	v_ashrrev_i32_e32 v205, 31, v204
	v_ashrrev_i32_e32 v203, 31, v202
	v_ashrrev_i32_e32 v201, 31, v200
	v_lshlrev_b64 v[130:131], 12, v[204:205]
	v_lshlrev_b64 v[132:133], 12, v[202:203]
	v_lshlrev_b64 v[134:135], 12, v[200:201]
	v_lshl_add_u64 v[130:131], v[196:197], 0, v[130:131]
	v_lshl_add_u64 v[132:133], v[196:197], 0, v[132:133]
	v_lshl_add_u64 v[134:135], v[196:197], 0, v[134:135]
	global_load_dwordx4 v[170:173], v[130:131], off offset:16 nt
	global_load_dwordx4 v[174:177], v[130:131], off nt
	global_load_dwordx4 v[162:165], v[130:131], off offset:528 nt
	global_load_dwordx4 v[166:169], v[130:131], off offset:512 nt
	global_load_dwordx4 v[154:157], v[132:133], off offset:16 nt
	global_load_dwordx4 v[158:161], v[132:133], off nt
	global_load_dwordx4 v[146:149], v[132:133], off offset:528 nt
	global_load_dwordx4 v[150:153], v[132:133], off offset:512 nt
	global_load_dwordx4 v[138:141], v[134:135], off offset:16 nt
	global_load_dwordx4 v[142:145], v[134:135], off nt
	s_nop 0
	global_load_dwordx4 v[130:133], v[134:135], off offset:528 nt
	s_nop 0
	global_load_dwordx4 v[134:137], v[134:135], off offset:512 nt
	v_and_b32_e32 v230, 64, v210
	v_xor_b32_e32 v213, 16, v210
	v_add_u32_e32 v233, 64, v230
	v_xor_b32_e32 v232, 32, v210
	v_lshlrev_b64 v[230:231], 10, v[198:199]
	v_cmp_lt_i32_e32 vcc, v213, v233
	v_lshl_add_u64 v[230:231], v[230:231], 0, v[194:195]
	s_lshl_b32 s18, s16, 2
	v_cndmask_b32_e32 v213, v210, v213, vcc
	v_cmp_lt_i32_e32 vcc, v232, v233
	v_lshlrev_b32_e32 v213, 2, v213
	s_ashr_i32 s19, s18, 31
	v_cndmask_b32_e32 v236, v210, v232, vcc
	v_lshl_add_u64 v[232:233], v[230:231], 2, s[62:63]
	v_lshlrev_b64 v[230:231], 1, v[230:231]
	v_lshl_add_u64 v[234:235], s[2:3], 0, v[230:231]
	v_or_b32_e32 v230, 0x100, v230
	s_waitcnt vmcnt(0)
	v_pk_fma_f32 v[128:129], v[128:129], 0.5, v[216:217] op_sel_hi:[1,0,1]
	v_pk_fma_f32 v[126:127], v[126:127], 0.5, v[214:215] op_sel_hi:[1,0,1]
	v_pk_fma_f32 v[120:121], v[120:121], 0.5, v[224:225] op_sel_hi:[1,0,1]
	v_pk_fma_f32 v[118:119], v[118:119], 0.5, v[222:223] op_sel_hi:[1,0,1]
	v_pk_fma_f32 v[124:125], v[124:125], 0.5, v[220:221] op_sel_hi:[1,0,1]
	v_pk_fma_f32 v[122:123], v[122:123], 0.5, v[218:219] op_sel_hi:[1,0,1]
	v_pk_fma_f32 v[114:115], v[114:115], 0.5, v[226:227] op_sel_hi:[1,0,1]
	global_store_dwordx4 v[232:233], v[126:129], off nt
	global_store_dwordx4 v[232:233], v[122:125], off offset:16 nt
	v_cvt_pk_bf16_f32 v214, v126, v127
	v_cvt_pk_bf16_f32 v215, v128, v129
	v_mul_f32_e32 v218, v119, v119
	v_mul_f32_e32 v127, v127, v127
	v_mul_f32_e32 v129, v129, v129
	v_mul_f32_e32 v219, v121, v121
	v_pk_fma_f32 v[116:117], v[116:117], 0.5, v[228:229] op_sel_hi:[1,0,1]
	v_cvt_pk_bf16_f32 v216, v122, v123
	v_cvt_pk_bf16_f32 v217, v124, v125
	v_mul_f32_e32 v123, v123, v123
	v_mul_f32_e32 v125, v125, v125
	v_mul_f32_e32 v220, v115, v115
	v_fmac_f32_e32 v127, v126, v126
	v_fmac_f32_e32 v129, v128, v128
	v_fmac_f32_e32 v218, v118, v118
	v_fmac_f32_e32 v219, v120, v120
	v_mul_f32_e32 v221, v117, v117
	v_fmac_f32_e32 v123, v122, v122
	v_fmac_f32_e32 v125, v124, v124
	v_fmac_f32_e32 v220, v114, v114
	v_add_f32_e32 v122, v127, v129
	v_add_f32_e32 v124, v218, v219
	v_fmac_f32_e32 v221, v116, v116
	v_add_f32_e32 v122, v122, v123
	v_add_f32_e32 v123, v124, v220
	v_add_f32_e32 v122, v125, v122
	v_add_f32_e32 v123, v221, v123
	v_add_f32_e32 v122, v122, v123
	ds_bpermute_b32 v123, v213, v122
	global_store_dwordx4 v[234:235], v[214:217], off
	global_store_dwordx4 v[232:233], v[118:121], off offset:512 nt
	global_store_dwordx4 v[232:233], v[114:117], off offset:528 nt
	s_nop 0
	v_cvt_pk_bf16_f32 v118, v118, v119
	v_cvt_pk_bf16_f32 v119, v120, v121
	v_cvt_pk_bf16_f32 v120, v114, v115
	v_cvt_pk_bf16_f32 v121, v116, v117
	s_waitcnt lgkmcnt(0)
	v_add_f32_e32 v114, v122, v123
	v_lshlrev_b32_e32 v122, 2, v236
	ds_bpermute_b32 v115, v122, v114
	v_lshl_add_u64 v[116:117], s[2:3], 0, v[230:231]
	global_store_dwordx4 v[116:117], v[118:121], off
	s_and_saveexec_b64 s[20:21], s[4:5]
	s_cbranch_execz .LBB0_297
	s_waitcnt lgkmcnt(0)
	v_add_f32_e32 v116, v114, v115
	v_lshlrev_b64 v[114:115], 6, v[198:199]
	v_lshl_add_u64 v[114:115], s[12:13], 0, v[114:115]
	v_lshl_add_u64 v[114:115], s[18:19], 2, v[114:115]
	s_lshl_b32 s16, s36, 2
	v_lshl_add_u64 v[114:115], v[114:115], 0, s[16:17]
	global_store_dword v[114:115], v116, off

.LBB0_338:
	ds_read_b128 v[82:85], v165
	ds_read_b128 v[86:89], v165 offset:1024
	ds_read_b128 v[90:93], v165 offset:2048
	ds_read_b128 v[94:97], v165 offset:3072
	ds_read_b128 v[146:149], v184
	ds_read_b128 v[150:153], v184 offset:1024
	ds_read_b128 v[180:183], v184 offset:2048
	ds_read_b128 v[194:197], v184 offset:3072
	s_add_u32 s12, s10, 0xfffc0080
	s_addc_u32 s13, s11, -1
	s_cmp_eq_u32 s72, 12
	s_cselect_b32 s15, s1, s13
	s_cselect_b32 s14, s3, s12
	s_cselect_b32 s13, s16, s35
	s_cselect_b32 s12, s17, s31
	v_lshl_add_u64 v[230:231], s[10:11], 0, v[170:171]
	s_add_i32 m0, s44, 0xc000
	ds_read_b128 v[198:201], v185
	ds_read_b128 v[202:205], v185 offset:1024
	ds_read_b128 v[206:209], v185 offset:2048
	ds_read_b128 v[210:213], v185 offset:3072
	ds_read_b128 v[214:217], v185 offset:4096
	ds_read_b128 v[218:221], v185 offset:5120
	ds_read_b128 v[222:225], v185 offset:6144
	ds_read_b128 v[226:229], v185 offset:7168
	global_load_lds_dwordx4 v[230:231], off
	v_lshl_add_u64 v[230:231], s[10:11], 0, v[172:173]
	s_add_i32 m0, s44, 0xe000
	s_nop 0
	global_load_lds_dwordx4 v[230:231], off
	s_waitcnt vmcnt(8)
	s_waitcnt lgkmcnt(0)
	s_barrier
	s_setprio 1
	v_mfma_f32_16x16x32_bf16 v[62:65], v[82:85], v[198:201], v[62:65]
	v_mfma_f32_16x16x32_bf16 v[58:61], v[90:93], v[198:201], v[58:61]
	v_mfma_f32_16x16x32_bf16 v[54:57], v[82:85], v[206:209], v[54:57]
	v_mfma_f32_16x16x32_bf16 v[50:53], v[90:93], v[206:209], v[50:53]
	v_mfma_f32_16x16x32_bf16 v[46:49], v[82:85], v[214:217], v[46:49]
	v_mfma_f32_16x16x32_bf16 v[42:45], v[90:93], v[214:217], v[42:45]
	v_mfma_f32_16x16x32_bf16 v[38:41], v[82:85], v[222:225], v[38:41]
	v_mfma_f32_16x16x32_bf16 v[34:37], v[90:93], v[222:225], v[34:37]
	v_mfma_f32_16x16x32_bf16 v[62:65], v[86:89], v[202:205], v[62:65]
	v_mfma_f32_16x16x32_bf16 v[58:61], v[94:97], v[202:205], v[58:61]
	v_mfma_f32_16x16x32_bf16 v[54:57], v[86:89], v[210:213], v[54:57]
	v_mfma_f32_16x16x32_bf16 v[50:53], v[94:97], v[210:213], v[50:53]
	v_mfma_f32_16x16x32_bf16 v[46:49], v[86:89], v[218:221], v[46:49]
	v_mfma_f32_16x16x32_bf16 v[42:45], v[94:97], v[218:221], v[42:45]
	v_mfma_f32_16x16x32_bf16 v[38:41], v[86:89], v[226:229], v[38:41]
	v_mfma_f32_16x16x32_bf16 v[34:37], v[94:97], v[226:229], v[34:37]
	v_mfma_f32_16x16x32_bf16 v[142:145], v[146:149], v[198:201], v[142:145]
	v_mfma_f32_16x16x32_bf16 v[138:141], v[180:183], v[198:201], v[138:141]
	v_mfma_f32_16x16x32_bf16 v[134:137], v[146:149], v[206:209], v[134:137]
	v_mfma_f32_16x16x32_bf16 v[130:133], v[180:183], v[206:209], v[130:133]
	v_mfma_f32_16x16x32_bf16 v[126:129], v[146:149], v[214:217], v[126:129]
	v_mfma_f32_16x16x32_bf16 v[122:125], v[180:183], v[214:217], v[122:125]
	v_mfma_f32_16x16x32_bf16 v[118:121], v[146:149], v[222:225], v[118:121]
	v_mfma_f32_16x16x32_bf16 v[114:117], v[180:183], v[222:225], v[114:117]
	v_mfma_f32_16x16x32_bf16 v[142:145], v[150:153], v[202:205], v[142:145]
	v_mfma_f32_16x16x32_bf16 v[138:141], v[194:197], v[202:205], v[138:141]
	v_mfma_f32_16x16x32_bf16 v[134:137], v[150:153], v[210:213], v[134:137]
	v_mfma_f32_16x16x32_bf16 v[130:133], v[194:197], v[210:213], v[130:133]
	v_mfma_f32_16x16x32_bf16 v[126:129], v[150:153], v[218:221], v[126:129]
	v_mfma_f32_16x16x32_bf16 v[122:125], v[194:197], v[218:221], v[122:125]
	v_mfma_f32_16x16x32_bf16 v[118:121], v[150:153], v[226:229], v[118:121]
	v_mfma_f32_16x16x32_bf16 v[114:117], v[194:197], v[226:229], v[114:117]
	s_setprio 0
	s_barrier
	s_add_i32 s73, s56, s43
	v_lshl_add_u64 v[230:231], s[12:13], 0, v[156:157]
	s_mov_b32 m0, s73
	ds_read_b128 v[198:201], v185 offset:16384
	ds_read_b128 v[202:205], v185 offset:17408
	ds_read_b128 v[206:209], v185 offset:18432
	ds_read_b128 v[210:213], v185 offset:19456
	ds_read_b128 v[214:217], v185 offset:20480
	ds_read_b128 v[218:221], v185 offset:21504
	ds_read_b128 v[222:225], v185 offset:22528
	ds_read_b128 v[226:229], v185 offset:23552
	global_load_lds_dwordx4 v[230:231], off
	s_add_i32 m0, s73, 0x2000
	s_add_u32 s74, s12, 0x40000
	v_lshl_add_u64 v[232:233], s[12:13], 0, v[160:161]
	s_addc_u32 s75, s13, 0
	s_add_i32 s73, s57, s43
	global_load_lds_dwordx4 v[232:233], off
	v_lshl_add_u64 v[234:235], s[74:75], 0, v[156:157]
	s_mov_b32 m0, s73
	v_lshl_add_u64 v[236:237], s[14:15], 0, v[158:159]
	global_load_lds_dwordx4 v[234:235], off
	v_lshl_add_u64 v[234:235], s[74:75], 0, v[160:161]
	s_add_i32 m0, s73, 0x2000
	s_nop 0
	global_load_lds_dwordx4 v[234:235], off
	s_waitcnt vmcnt(6)
	s_waitcnt lgkmcnt(0)
	s_barrier
	s_setprio 1
	v_mfma_f32_16x16x32_bf16 v[30:33], v[82:85], v[198:201], v[30:33]
	v_mfma_f32_16x16x32_bf16 v[26:29], v[90:93], v[198:201], v[26:29]
	v_mfma_f32_16x16x32_bf16 v[22:25], v[82:85], v[206:209], v[22:25]
	v_mfma_f32_16x16x32_bf16 v[18:21], v[90:93], v[206:209], v[18:21]
	v_lshl_add_u64 v[234:235], s[14:15], 0, v[154:155]
	s_mov_b32 m0, s44
	s_nop 0
	global_load_lds_dwordx4 v[234:235], off
	v_mfma_f32_16x16x32_bf16 v[14:17], v[82:85], v[214:217], v[14:17]
	v_mfma_f32_16x16x32_bf16 v[10:13], v[90:93], v[214:217], v[10:13]
	v_mfma_f32_16x16x32_bf16 v[6:9], v[82:85], v[222:225], v[6:9]
	v_mfma_f32_16x16x32_bf16 v[2:5], v[90:93], v[222:225], v[2:5]
	v_mfma_f32_16x16x32_bf16 v[30:33], v[86:89], v[202:205], v[30:33]
	v_mfma_f32_16x16x32_bf16 v[26:29], v[94:97], v[202:205], v[26:29]
	v_mfma_f32_16x16x32_bf16 v[22:25], v[86:89], v[210:213], v[22:25]
	v_mfma_f32_16x16x32_bf16 v[18:21], v[94:97], v[210:213], v[18:21]
	s_mov_b32 m0, s45
	s_nop 0
	global_load_lds_dwordx4 v[236:237], off
	v_mfma_f32_16x16x32_bf16 v[14:17], v[86:89], v[218:221], v[14:17]
	v_mfma_f32_16x16x32_bf16 v[10:13], v[94:97], v[218:221], v[10:13]
	v_mfma_f32_16x16x32_bf16 v[6:9], v[86:89], v[226:229], v[6:9]
	v_mfma_f32_16x16x32_bf16 v[2:5], v[94:97], v[226:229], v[2:5]
	v_mfma_f32_16x16x32_bf16 v[78:81], v[146:149], v[214:217], v[78:81]
	v_mfma_f32_16x16x32_bf16 v[74:77], v[180:183], v[214:217], v[74:77]
	v_mfma_f32_16x16x32_bf16 v[70:73], v[146:149], v[222:225], v[70:73]
	v_mfma_f32_16x16x32_bf16 v[66:69], v[180:183], v[222:225], v[66:69]
	v_mfma_f32_16x16x32_bf16 v[82:85], v[146:149], v[198:201], v[110:113]
	v_mfma_f32_16x16x32_bf16 v[86:89], v[180:183], v[198:201], v[106:109]
	v_mfma_f32_16x16x32_bf16 v[90:93], v[146:149], v[206:209], v[102:105]
	v_mfma_f32_16x16x32_bf16 v[94:97], v[180:183], v[206:209], v[98:101]
	v_mfma_f32_16x16x32_bf16 v[78:81], v[150:153], v[218:221], v[78:81]
	v_mfma_f32_16x16x32_bf16 v[74:77], v[194:197], v[218:221], v[74:77]
	v_mfma_f32_16x16x32_bf16 v[70:73], v[150:153], v[226:229], v[70:73]
	v_mfma_f32_16x16x32_bf16 v[66:69], v[194:197], v[226:229], v[66:69]
	v_mfma_f32_16x16x32_bf16 v[82:85], v[150:153], v[202:205], v[82:85]
	v_mfma_f32_16x16x32_bf16 v[86:89], v[194:197], v[202:205], v[86:89]
	v_mfma_f32_16x16x32_bf16 v[90:93], v[150:153], v[210:213], v[90:93]
	v_mfma_f32_16x16x32_bf16 v[94:97], v[194:197], v[210:213], v[94:97]
	s_setprio 0
	s_barrier
	ds_read_b128 v[98:101], v189
	ds_read_b128 v[102:105], v189 offset:1024
	ds_read_b128 v[106:109], v189 offset:2048
	ds_read_b128 v[110:113], v189 offset:3072
	ds_read_b128 v[146:149], v190
	ds_read_b128 v[150:153], v190 offset:1024
	ds_read_b128 v[180:183], v190 offset:2048
	ds_read_b128 v[194:197], v190 offset:3072
	s_add_u32 s14, s14, 0x40000
	s_addc_u32 s15, s15, 0
	s_mov_b32 m0, s46
	v_lshl_add_u64 v[238:239], s[14:15], 0, v[154:155]
	ds_read_b128 v[198:201], v185 offset:32768
	ds_read_b128 v[202:205], v185 offset:33792
	ds_read_b128 v[206:209], v185 offset:34816
	ds_read_b128 v[210:213], v185 offset:35840
	ds_read_b128 v[214:217], v185 offset:36864
	ds_read_b128 v[218:221], v185 offset:37888
	ds_read_b128 v[222:225], v185 offset:38912
	ds_read_b128 v[226:229], v185 offset:39936
	global_load_lds_dwordx4 v[238:239], off
	v_lshl_add_u64 v[238:239], s[14:15], 0, v[158:159]
	s_mov_b32 m0, s47
	s_nop 0
	global_load_lds_dwordx4 v[238:239], off
	s_waitcnt vmcnt(8)
	s_waitcnt lgkmcnt(0)
	s_barrier
	s_setprio 1
	v_mfma_f32_16x16x32_bf16 v[62:65], v[98:101], v[198:201], v[62:65]
	v_mfma_f32_16x16x32_bf16 v[58:61], v[106:109], v[198:201], v[58:61]
	v_mfma_f32_16x16x32_bf16 v[54:57], v[98:101], v[206:209], v[54:57]
	v_mfma_f32_16x16x32_bf16 v[50:53], v[106:109], v[206:209], v[50:53]
	v_mfma_f32_16x16x32_bf16 v[46:49], v[98:101], v[214:217], v[46:49]
	v_mfma_f32_16x16x32_bf16 v[42:45], v[106:109], v[214:217], v[42:45]
	v_mfma_f32_16x16x32_bf16 v[38:41], v[98:101], v[222:225], v[38:41]
	v_mfma_f32_16x16x32_bf16 v[34:37], v[106:109], v[222:225], v[34:37]
	v_mfma_f32_16x16x32_bf16 v[62:65], v[102:105], v[202:205], v[62:65]
	v_mfma_f32_16x16x32_bf16 v[58:61], v[110:113], v[202:205], v[58:61]
	v_mfma_f32_16x16x32_bf16 v[54:57], v[102:105], v[210:213], v[54:57]
	v_mfma_f32_16x16x32_bf16 v[50:53], v[110:113], v[210:213], v[50:53]
	v_mfma_f32_16x16x32_bf16 v[46:49], v[102:105], v[218:221], v[46:49]
	v_mfma_f32_16x16x32_bf16 v[42:45], v[110:113], v[218:221], v[42:45]
	v_mfma_f32_16x16x32_bf16 v[38:41], v[102:105], v[226:229], v[38:41]
	v_mfma_f32_16x16x32_bf16 v[34:37], v[110:113], v[226:229], v[34:37]
	v_mfma_f32_16x16x32_bf16 v[142:145], v[146:149], v[198:201], v[142:145]
	v_mfma_f32_16x16x32_bf16 v[138:141], v[180:183], v[198:201], v[138:141]
	v_mfma_f32_16x16x32_bf16 v[134:137], v[146:149], v[206:209], v[134:137]
	v_mfma_f32_16x16x32_bf16 v[130:133], v[180:183], v[206:209], v[130:133]
	v_mfma_f32_16x16x32_bf16 v[126:129], v[146:149], v[214:217], v[126:129]
	v_mfma_f32_16x16x32_bf16 v[122:125], v[180:183], v[214:217], v[122:125]
	v_mfma_f32_16x16x32_bf16 v[118:121], v[146:149], v[222:225], v[118:121]
	v_mfma_f32_16x16x32_bf16 v[114:117], v[180:183], v[222:225], v[114:117]
	v_mfma_f32_16x16x32_bf16 v[142:145], v[150:153], v[202:205], v[142:145]
	v_mfma_f32_16x16x32_bf16 v[138:141], v[194:197], v[202:205], v[138:141]
	v_mfma_f32_16x16x32_bf16 v[134:137], v[150:153], v[210:213], v[134:137]
	v_mfma_f32_16x16x32_bf16 v[130:133], v[194:197], v[210:213], v[130:133]
	v_mfma_f32_16x16x32_bf16 v[126:129], v[150:153], v[218:221], v[126:129]
	v_mfma_f32_16x16x32_bf16 v[122:125], v[194:197], v[218:221], v[122:125]
	v_mfma_f32_16x16x32_bf16 v[118:121], v[150:153], v[226:229], v[118:121]
	v_mfma_f32_16x16x32_bf16 v[114:117], v[194:197], v[226:229], v[114:117]
	s_setprio 0
	s_barrier
	s_add_i32 s14, s70, s43
	v_lshl_add_u64 v[230:231], v[230:231], 0, s[26:27]
	s_mov_b32 m0, s14
	ds_read_b128 v[198:201], v185 offset:49152
	ds_read_b128 v[202:205], v185 offset:50176
	ds_read_b128 v[206:209], v185 offset:51200
	ds_read_b128 v[210:213], v185 offset:52224
	ds_read_b128 v[214:217], v185 offset:53248
	ds_read_b128 v[218:221], v185 offset:54272
	ds_read_b128 v[222:225], v185 offset:55296
	ds_read_b128 v[226:229], v185 offset:56320
	global_load_lds_dwordx4 v[230:231], off
	s_add_i32 m0, s14, 0x2000
	s_add_u32 s12, s12, 0x40080
	v_lshl_add_u64 v[230:231], v[232:233], 0, s[26:27]
	s_addc_u32 s13, s13, 0
	s_add_i32 s14, s71, s43
	global_load_lds_dwordx4 v[230:231], off
	v_lshl_add_u64 v[230:231], s[12:13], 0, v[156:157]
	s_mov_b32 m0, s14
	s_nop 0
	global_load_lds_dwordx4 v[230:231], off
	v_lshl_add_u64 v[230:231], s[12:13], 0, v[160:161]
	s_add_i32 m0, s14, 0x2000
	s_nop 0
	global_load_lds_dwordx4 v[230:231], off
	s_waitcnt vmcnt(6)
	s_waitcnt lgkmcnt(0)
	s_barrier
	s_setprio 1
	v_mfma_f32_16x16x32_bf16 v[30:33], v[98:101], v[198:201], v[30:33]
	v_mfma_f32_16x16x32_bf16 v[26:29], v[106:109], v[198:201], v[26:29]
	v_mfma_f32_16x16x32_bf16 v[22:25], v[98:101], v[206:209], v[22:25]
	v_mfma_f32_16x16x32_bf16 v[18:21], v[106:109], v[206:209], v[18:21]
	v_lshl_add_u64 v[230:231], v[234:235], 0, s[26:27]
	s_mov_b32 m0, s50
	s_nop 0
	global_load_lds_dwordx4 v[230:231], off
	v_mfma_f32_16x16x32_bf16 v[14:17], v[98:101], v[214:217], v[14:17]
	v_mfma_f32_16x16x32_bf16 v[10:13], v[106:109], v[214:217], v[10:13]
	v_mfma_f32_16x16x32_bf16 v[6:9], v[98:101], v[222:225], v[6:9]
	v_mfma_f32_16x16x32_bf16 v[2:5], v[106:109], v[222:225], v[2:5]
	v_mfma_f32_16x16x32_bf16 v[30:33], v[102:105], v[202:205], v[30:33]
	v_mfma_f32_16x16x32_bf16 v[26:29], v[110:113], v[202:205], v[26:29]
	v_mfma_f32_16x16x32_bf16 v[22:25], v[102:105], v[210:213], v[22:25]
	v_mfma_f32_16x16x32_bf16 v[18:21], v[110:113], v[210:213], v[18:21]
	v_lshl_add_u64 v[230:231], v[236:237], 0, s[26:27]
	s_mov_b32 m0, s51
	s_nop 0
	global_load_lds_dwordx4 v[230:231], off
	v_mfma_f32_16x16x32_bf16 v[14:17], v[102:105], v[218:221], v[14:17]
	v_mfma_f32_16x16x32_bf16 v[10:13], v[110:113], v[218:221], v[10:13]
	v_mfma_f32_16x16x32_bf16 v[6:9], v[102:105], v[226:229], v[6:9]
	v_mfma_f32_16x16x32_bf16 v[2:5], v[110:113], v[226:229], v[2:5]
	v_mfma_f32_16x16x32_bf16 v[82:85], v[146:149], v[198:201], v[82:85]
	v_mfma_f32_16x16x32_bf16 v[110:113], v[150:153], v[202:205], v[82:85]
	v_mfma_f32_16x16x32_bf16 v[82:85], v[180:183], v[198:201], v[86:89]
	v_mfma_f32_16x16x32_bf16 v[106:109], v[194:197], v[202:205], v[82:85]
	v_mfma_f32_16x16x32_bf16 v[82:85], v[146:149], v[206:209], v[90:93]
	v_mfma_f32_16x16x32_bf16 v[102:105], v[150:153], v[210:213], v[82:85]
	v_mfma_f32_16x16x32_bf16 v[82:85], v[180:183], v[206:209], v[94:97]
	v_mfma_f32_16x16x32_bf16 v[78:81], v[146:149], v[214:217], v[78:81]
	v_mfma_f32_16x16x32_bf16 v[74:77], v[180:183], v[214:217], v[74:77]
	v_mfma_f32_16x16x32_bf16 v[70:73], v[146:149], v[222:225], v[70:73]
	v_mfma_f32_16x16x32_bf16 v[66:69], v[180:183], v[222:225], v[66:69]
	v_mfma_f32_16x16x32_bf16 v[98:101], v[194:197], v[210:213], v[82:85]
	v_mfma_f32_16x16x32_bf16 v[78:81], v[150:153], v[218:221], v[78:81]
	v_mfma_f32_16x16x32_bf16 v[74:77], v[194:197], v[218:221], v[74:77]
	v_mfma_f32_16x16x32_bf16 v[70:73], v[150:153], v[226:229], v[70:73]
	v_mfma_f32_16x16x32_bf16 v[66:69], v[194:197], v[226:229], v[66:69]
	s_setprio 0
	s_barrier
	s_add_i32 s72, s72, 2
	s_add_u32 s10, s10, 0x100
	s_addc_u32 s11, s11, 0
	s_add_u32 s31, s31, 0x100
	s_addc_u32 s35, s35, 0
	s_cmp_gt_u32 s72, 13
	s_cbranch_scc0 .LBB0_338
	s_and_b64 vcc, exec, s[28:29]
	s_cbranch_vccz .LBB0_341
	s_barrier

.LBB0_2387:
	ds_read_b128 v[130:133], v213
	ds_read_b128 v[134:137], v213 offset:1024
	ds_read_b128 v[138:141], v213 offset:2048
	ds_read_b128 v[142:145], v213 offset:3072
	ds_read_b128 v[146:149], v214
	ds_read_b128 v[150:153], v214 offset:1024
	ds_read_b128 v[154:157], v214 offset:2048
	ds_read_b128 v[158:161], v214 offset:3072
	s_add_u32 s26, s24, 0xfffc0080
	s_addc_u32 s27, s25, -1
	s_cmp_eq_u32 s55, 12
	s_cselect_b32 s29, s17, s27
	s_cselect_b32 s28, s23, s26
	s_cselect_b32 s27, s15, s54
	s_cselect_b32 s26, s52, s53
	v_lshl_add_u64 v[210:211], s[24:25], 0, v[186:187]
	s_add_i32 m0, s38, 0xc000
	ds_read_b128 v[162:165], v215
	ds_read_b128 v[166:169], v215 offset:1024
	ds_read_b128 v[170:173], v215 offset:2048
	ds_read_b128 v[174:177], v215 offset:3072
	ds_read_b128 v[194:197], v215 offset:4096
	ds_read_b128 v[198:201], v215 offset:5120
	ds_read_b128 v[202:205], v215 offset:6144
	ds_read_b128 v[206:209], v215 offset:7168
	global_load_lds_dwordx4 v[210:211], off
	v_lshl_add_u64 v[210:211], s[24:25], 0, v[188:189]
	s_add_i32 m0, s38, 0xe000
	s_nop 0
	global_load_lds_dwordx4 v[210:211], off
	s_waitcnt vmcnt(8)
	s_waitcnt lgkmcnt(0)
	s_barrier
	s_setprio 1
	v_mfma_f32_16x16x32_bf16 v[126:129], v[130:133], v[162:165], v[126:129]
	v_mfma_f32_16x16x32_bf16 v[122:125], v[138:141], v[162:165], v[122:125]
	v_mfma_f32_16x16x32_bf16 v[110:113], v[130:133], v[170:173], v[110:113]
	v_mfma_f32_16x16x32_bf16 v[106:109], v[138:141], v[170:173], v[106:109]
	v_mfma_f32_16x16x32_bf16 v[94:97], v[130:133], v[194:197], v[94:97]
	v_mfma_f32_16x16x32_bf16 v[90:93], v[138:141], v[194:197], v[90:93]
	v_mfma_f32_16x16x32_bf16 v[78:81], v[130:133], v[202:205], v[78:81]
	v_mfma_f32_16x16x32_bf16 v[74:77], v[138:141], v[202:205], v[74:77]
	v_mfma_f32_16x16x32_bf16 v[126:129], v[134:137], v[166:169], v[126:129]
	v_mfma_f32_16x16x32_bf16 v[122:125], v[142:145], v[166:169], v[122:125]
	v_mfma_f32_16x16x32_bf16 v[110:113], v[134:137], v[174:177], v[110:113]
	v_mfma_f32_16x16x32_bf16 v[106:109], v[142:145], v[174:177], v[106:109]
	v_mfma_f32_16x16x32_bf16 v[94:97], v[134:137], v[198:201], v[94:97]
	v_mfma_f32_16x16x32_bf16 v[90:93], v[142:145], v[198:201], v[90:93]
	v_mfma_f32_16x16x32_bf16 v[78:81], v[134:137], v[206:209], v[78:81]
	v_mfma_f32_16x16x32_bf16 v[74:77], v[142:145], v[206:209], v[74:77]
	v_mfma_f32_16x16x32_bf16 v[118:121], v[146:149], v[162:165], v[118:121]
	v_mfma_f32_16x16x32_bf16 v[114:117], v[154:157], v[162:165], v[114:117]
	v_mfma_f32_16x16x32_bf16 v[102:105], v[146:149], v[170:173], v[102:105]
	v_mfma_f32_16x16x32_bf16 v[98:101], v[154:157], v[170:173], v[98:101]
	v_mfma_f32_16x16x32_bf16 v[86:89], v[146:149], v[194:197], v[86:89]
	v_mfma_f32_16x16x32_bf16 v[82:85], v[154:157], v[194:197], v[82:85]
	v_mfma_f32_16x16x32_bf16 v[70:73], v[146:149], v[202:205], v[70:73]
	v_mfma_f32_16x16x32_bf16 v[66:69], v[154:157], v[202:205], v[66:69]
	v_mfma_f32_16x16x32_bf16 v[118:121], v[150:153], v[166:169], v[118:121]
	v_mfma_f32_16x16x32_bf16 v[114:117], v[158:161], v[166:169], v[114:117]
	v_mfma_f32_16x16x32_bf16 v[102:105], v[150:153], v[174:177], v[102:105]
	v_mfma_f32_16x16x32_bf16 v[98:101], v[158:161], v[174:177], v[98:101]
	v_mfma_f32_16x16x32_bf16 v[86:89], v[150:153], v[198:201], v[86:89]
	v_mfma_f32_16x16x32_bf16 v[82:85], v[158:161], v[198:201], v[82:85]
	v_mfma_f32_16x16x32_bf16 v[70:73], v[150:153], v[206:209], v[70:73]
	v_mfma_f32_16x16x32_bf16 v[66:69], v[158:161], v[206:209], v[66:69]
	s_setprio 0
	s_barrier
	s_add_i32 s56, s47, s37
	v_lshl_add_u64 v[210:211], s[26:27], 0, v[180:181]
	s_mov_b32 m0, s56
	ds_read_b128 v[162:165], v215 offset:16384
	ds_read_b128 v[166:169], v215 offset:17408
	ds_read_b128 v[170:173], v215 offset:18432
	ds_read_b128 v[174:177], v215 offset:19456
	ds_read_b128 v[194:197], v215 offset:20480
	ds_read_b128 v[198:201], v215 offset:21504
	ds_read_b128 v[202:205], v215 offset:22528
	ds_read_b128 v[206:209], v215 offset:23552
	global_load_lds_dwordx4 v[210:211], off
	s_add_i32 m0, s56, 0x2000
	s_add_u32 s56, s26, 0x40000
	v_lshl_add_u64 v[220:221], s[26:27], 0, v[184:185]
	s_addc_u32 s57, s27, 0
	s_add_i32 s58, s48, s37
	global_load_lds_dwordx4 v[220:221], off
	v_lshl_add_u64 v[222:223], s[56:57], 0, v[180:181]
	s_mov_b32 m0, s58
	v_lshl_add_u64 v[224:225], s[28:29], 0, v[182:183]
	global_load_lds_dwordx4 v[222:223], off
	v_lshl_add_u64 v[222:223], s[56:57], 0, v[184:185]
	s_add_i32 m0, s58, 0x2000
	s_nop 0
	global_load_lds_dwordx4 v[222:223], off
	s_waitcnt vmcnt(6)
	s_waitcnt lgkmcnt(0)
	s_barrier
	s_setprio 1
	v_mfma_f32_16x16x32_bf16 v[62:65], v[130:133], v[162:165], v[62:65]
	v_mfma_f32_16x16x32_bf16 v[58:61], v[138:141], v[162:165], v[58:61]
	v_mfma_f32_16x16x32_bf16 v[46:49], v[130:133], v[170:173], v[46:49]
	v_mfma_f32_16x16x32_bf16 v[42:45], v[138:141], v[170:173], v[42:45]
	v_lshl_add_u64 v[222:223], s[28:29], 0, v[178:179]
	s_mov_b32 m0, s38
	s_nop 0
	global_load_lds_dwordx4 v[222:223], off
	v_mfma_f32_16x16x32_bf16 v[30:33], v[130:133], v[194:197], v[30:33]
	v_mfma_f32_16x16x32_bf16 v[26:29], v[138:141], v[194:197], v[26:29]
	v_mfma_f32_16x16x32_bf16 v[14:17], v[130:133], v[202:205], v[14:17]
	v_mfma_f32_16x16x32_bf16 v[10:13], v[138:141], v[202:205], v[10:13]
	v_mfma_f32_16x16x32_bf16 v[62:65], v[134:137], v[166:169], v[62:65]
	v_mfma_f32_16x16x32_bf16 v[58:61], v[142:145], v[166:169], v[58:61]
	v_mfma_f32_16x16x32_bf16 v[46:49], v[134:137], v[174:177], v[46:49]
	v_mfma_f32_16x16x32_bf16 v[42:45], v[142:145], v[174:177], v[42:45]
	s_mov_b32 m0, s39
	s_nop 0
	global_load_lds_dwordx4 v[224:225], off
	v_mfma_f32_16x16x32_bf16 v[30:33], v[134:137], v[198:201], v[30:33]
	v_mfma_f32_16x16x32_bf16 v[26:29], v[142:145], v[198:201], v[26:29]
	v_mfma_f32_16x16x32_bf16 v[14:17], v[134:137], v[206:209], v[14:17]
	v_mfma_f32_16x16x32_bf16 v[10:13], v[142:145], v[206:209], v[10:13]
	v_mfma_f32_16x16x32_bf16 v[54:57], v[146:149], v[162:165], v[54:57]
	v_mfma_f32_16x16x32_bf16 v[50:53], v[154:157], v[162:165], v[50:53]
	v_mfma_f32_16x16x32_bf16 v[38:41], v[146:149], v[170:173], v[38:41]
	v_mfma_f32_16x16x32_bf16 v[34:37], v[154:157], v[170:173], v[34:37]
	v_mfma_f32_16x16x32_bf16 v[22:25], v[146:149], v[194:197], v[22:25]
	v_mfma_f32_16x16x32_bf16 v[18:21], v[154:157], v[194:197], v[18:21]
	v_mfma_f32_16x16x32_bf16 v[6:9], v[146:149], v[202:205], v[6:9]
	v_mfma_f32_16x16x32_bf16 v[2:5], v[154:157], v[202:205], v[2:5]
	v_mfma_f32_16x16x32_bf16 v[54:57], v[150:153], v[166:169], v[54:57]
	v_mfma_f32_16x16x32_bf16 v[50:53], v[158:161], v[166:169], v[50:53]
	v_mfma_f32_16x16x32_bf16 v[38:41], v[150:153], v[174:177], v[38:41]
	v_mfma_f32_16x16x32_bf16 v[34:37], v[158:161], v[174:177], v[34:37]
	v_mfma_f32_16x16x32_bf16 v[22:25], v[150:153], v[198:201], v[22:25]
	v_mfma_f32_16x16x32_bf16 v[18:21], v[158:161], v[198:201], v[18:21]
	v_mfma_f32_16x16x32_bf16 v[6:9], v[150:153], v[206:209], v[6:9]
	v_mfma_f32_16x16x32_bf16 v[2:5], v[158:161], v[206:209], v[2:5]
	s_setprio 0
	s_barrier
	ds_read_b128 v[130:133], v217
	ds_read_b128 v[134:137], v217 offset:1024
	ds_read_b128 v[138:141], v217 offset:2048
	ds_read_b128 v[142:145], v217 offset:3072
	ds_read_b128 v[146:149], v218
	ds_read_b128 v[150:153], v218 offset:1024
	ds_read_b128 v[154:157], v218 offset:2048
	ds_read_b128 v[158:161], v218 offset:3072
	s_add_u32 s28, s28, 0x40000
	s_addc_u32 s29, s29, 0
	s_mov_b32 m0, s40
	v_lshl_add_u64 v[226:227], s[28:29], 0, v[178:179]
	ds_read_b128 v[162:165], v215 offset:32768
	ds_read_b128 v[166:169], v215 offset:33792
	ds_read_b128 v[170:173], v215 offset:34816
	ds_read_b128 v[174:177], v215 offset:35840
	ds_read_b128 v[194:197], v215 offset:36864
	ds_read_b128 v[198:201], v215 offset:37888
	ds_read_b128 v[202:205], v215 offset:38912
	ds_read_b128 v[206:209], v215 offset:39936
	global_load_lds_dwordx4 v[226:227], off
	v_lshl_add_u64 v[226:227], s[28:29], 0, v[182:183]
	s_mov_b32 m0, s41
	s_nop 0
	global_load_lds_dwordx4 v[226:227], off
	s_waitcnt vmcnt(8)
	s_waitcnt lgkmcnt(0)
	s_barrier
	s_setprio 1
	v_mfma_f32_16x16x32_bf16 v[126:129], v[130:133], v[162:165], v[126:129]
	v_mfma_f32_16x16x32_bf16 v[122:125], v[138:141], v[162:165], v[122:125]
	v_mfma_f32_16x16x32_bf16 v[110:113], v[130:133], v[170:173], v[110:113]
	v_mfma_f32_16x16x32_bf16 v[106:109], v[138:141], v[170:173], v[106:109]
	v_mfma_f32_16x16x32_bf16 v[94:97], v[130:133], v[194:197], v[94:97]
	v_mfma_f32_16x16x32_bf16 v[90:93], v[138:141], v[194:197], v[90:93]
	v_mfma_f32_16x16x32_bf16 v[78:81], v[130:133], v[202:205], v[78:81]
	v_mfma_f32_16x16x32_bf16 v[74:77], v[138:141], v[202:205], v[74:77]
	v_mfma_f32_16x16x32_bf16 v[126:129], v[134:137], v[166:169], v[126:129]
	v_mfma_f32_16x16x32_bf16 v[122:125], v[142:145], v[166:169], v[122:125]
	v_mfma_f32_16x16x32_bf16 v[110:113], v[134:137], v[174:177], v[110:113]
	v_mfma_f32_16x16x32_bf16 v[106:109], v[142:145], v[174:177], v[106:109]
	v_mfma_f32_16x16x32_bf16 v[94:97], v[134:137], v[198:201], v[94:97]
	v_mfma_f32_16x16x32_bf16 v[90:93], v[142:145], v[198:201], v[90:93]
	v_mfma_f32_16x16x32_bf16 v[78:81], v[134:137], v[206:209], v[78:81]
	v_mfma_f32_16x16x32_bf16 v[74:77], v[142:145], v[206:209], v[74:77]
	v_mfma_f32_16x16x32_bf16 v[118:121], v[146:149], v[162:165], v[118:121]
	v_mfma_f32_16x16x32_bf16 v[114:117], v[154:157], v[162:165], v[114:117]
	v_mfma_f32_16x16x32_bf16 v[102:105], v[146:149], v[170:173], v[102:105]
	v_mfma_f32_16x16x32_bf16 v[98:101], v[154:157], v[170:173], v[98:101]
	v_mfma_f32_16x16x32_bf16 v[86:89], v[146:149], v[194:197], v[86:89]
	v_mfma_f32_16x16x32_bf16 v[82:85], v[154:157], v[194:197], v[82:85]
	v_mfma_f32_16x16x32_bf16 v[70:73], v[146:149], v[202:205], v[70:73]
	v_mfma_f32_16x16x32_bf16 v[66:69], v[154:157], v[202:205], v[66:69]
	v_mfma_f32_16x16x32_bf16 v[118:121], v[150:153], v[166:169], v[118:121]
	v_mfma_f32_16x16x32_bf16 v[114:117], v[158:161], v[166:169], v[114:117]
	v_mfma_f32_16x16x32_bf16 v[102:105], v[150:153], v[174:177], v[102:105]
	v_mfma_f32_16x16x32_bf16 v[98:101], v[158:161], v[174:177], v[98:101]
	v_mfma_f32_16x16x32_bf16 v[86:89], v[150:153], v[198:201], v[86:89]
	v_mfma_f32_16x16x32_bf16 v[82:85], v[158:161], v[198:201], v[82:85]
	v_mfma_f32_16x16x32_bf16 v[70:73], v[150:153], v[206:209], v[70:73]
	v_mfma_f32_16x16x32_bf16 v[66:69], v[158:161], v[206:209], v[66:69]
	s_setprio 0
	s_barrier
	s_add_i32 s28, s49, s37
	v_lshl_add_u64 v[210:211], v[210:211], 0, s[10:11]
	s_mov_b32 m0, s28
	ds_read_b128 v[162:165], v215 offset:49152
	ds_read_b128 v[166:169], v215 offset:50176
	ds_read_b128 v[170:173], v215 offset:51200
	ds_read_b128 v[174:177], v215 offset:52224
	ds_read_b128 v[194:197], v215 offset:53248
	ds_read_b128 v[198:201], v215 offset:54272
	ds_read_b128 v[202:205], v215 offset:55296
	ds_read_b128 v[206:209], v215 offset:56320
	global_load_lds_dwordx4 v[210:211], off
	s_add_i32 m0, s28, 0x2000
	s_add_u32 s26, s26, 0x40080
	v_lshl_add_u64 v[210:211], v[220:221], 0, s[10:11]
	s_addc_u32 s27, s27, 0
	s_add_i32 s28, s50, s37
	global_load_lds_dwordx4 v[210:211], off
	v_lshl_add_u64 v[210:211], s[26:27], 0, v[180:181]
	s_mov_b32 m0, s28
	s_nop 0
	global_load_lds_dwordx4 v[210:211], off
	v_lshl_add_u64 v[210:211], s[26:27], 0, v[184:185]
	s_add_i32 m0, s28, 0x2000
	s_nop 0
	global_load_lds_dwordx4 v[210:211], off
	s_waitcnt vmcnt(6)
	s_waitcnt lgkmcnt(0)
	s_barrier
	s_setprio 1
	v_mfma_f32_16x16x32_bf16 v[62:65], v[130:133], v[162:165], v[62:65]
	v_mfma_f32_16x16x32_bf16 v[58:61], v[138:141], v[162:165], v[58:61]
	v_mfma_f32_16x16x32_bf16 v[46:49], v[130:133], v[170:173], v[46:49]
	v_mfma_f32_16x16x32_bf16 v[42:45], v[138:141], v[170:173], v[42:45]
	v_lshl_add_u64 v[210:211], v[222:223], 0, s[10:11]
	s_mov_b32 m0, s43
	s_nop 0
	global_load_lds_dwordx4 v[210:211], off
	v_mfma_f32_16x16x32_bf16 v[30:33], v[130:133], v[194:197], v[30:33]
	v_mfma_f32_16x16x32_bf16 v[26:29], v[138:141], v[194:197], v[26:29]
	v_mfma_f32_16x16x32_bf16 v[14:17], v[130:133], v[202:205], v[14:17]
	v_mfma_f32_16x16x32_bf16 v[10:13], v[138:141], v[202:205], v[10:13]
	v_mfma_f32_16x16x32_bf16 v[62:65], v[134:137], v[166:169], v[62:65]
	v_mfma_f32_16x16x32_bf16 v[58:61], v[142:145], v[166:169], v[58:61]
	v_mfma_f32_16x16x32_bf16 v[46:49], v[134:137], v[174:177], v[46:49]
	v_mfma_f32_16x16x32_bf16 v[42:45], v[142:145], v[174:177], v[42:45]
	v_lshl_add_u64 v[210:211], v[224:225], 0, s[10:11]
	s_mov_b32 m0, s44
	s_nop 0
	global_load_lds_dwordx4 v[210:211], off
	v_mfma_f32_16x16x32_bf16 v[30:33], v[134:137], v[198:201], v[30:33]
	v_mfma_f32_16x16x32_bf16 v[26:29], v[142:145], v[198:201], v[26:29]
	v_mfma_f32_16x16x32_bf16 v[14:17], v[134:137], v[206:209], v[14:17]
	v_mfma_f32_16x16x32_bf16 v[10:13], v[142:145], v[206:209], v[10:13]
	v_mfma_f32_16x16x32_bf16 v[54:57], v[146:149], v[162:165], v[54:57]
	v_mfma_f32_16x16x32_bf16 v[50:53], v[154:157], v[162:165], v[50:53]
	v_mfma_f32_16x16x32_bf16 v[38:41], v[146:149], v[170:173], v[38:41]
	v_mfma_f32_16x16x32_bf16 v[34:37], v[154:157], v[170:173], v[34:37]
	v_mfma_f32_16x16x32_bf16 v[22:25], v[146:149], v[194:197], v[22:25]
	v_mfma_f32_16x16x32_bf16 v[18:21], v[154:157], v[194:197], v[18:21]
	v_mfma_f32_16x16x32_bf16 v[6:9], v[146:149], v[202:205], v[6:9]
	v_mfma_f32_16x16x32_bf16 v[2:5], v[154:157], v[202:205], v[2:5]
	v_mfma_f32_16x16x32_bf16 v[54:57], v[150:153], v[166:169], v[54:57]
	v_mfma_f32_16x16x32_bf16 v[50:53], v[158:161], v[166:169], v[50:53]
	v_mfma_f32_16x16x32_bf16 v[38:41], v[150:153], v[174:177], v[38:41]
	v_mfma_f32_16x16x32_bf16 v[34:37], v[158:161], v[174:177], v[34:37]
	v_mfma_f32_16x16x32_bf16 v[22:25], v[150:153], v[198:201], v[22:25]
	v_mfma_f32_16x16x32_bf16 v[18:21], v[158:161], v[198:201], v[18:21]
	v_mfma_f32_16x16x32_bf16 v[6:9], v[150:153], v[206:209], v[6:9]
	v_mfma_f32_16x16x32_bf16 v[2:5], v[158:161], v[206:209], v[2:5]
	s_setprio 0
	s_barrier
	s_add_i32 s55, s55, 2
	s_add_u32 s24, s24, 0x100
	s_addc_u32 s25, s25, 0
	s_add_u32 s53, s53, 0x100
	s_addc_u32 s54, s54, 0
	s_cmp_gt_u32 s55, 13
	s_cbranch_scc0 .LBB0_2387
	v_lshl_add_u32 v198, s22, 8, v1
	v_lshl_or_b32 v194, s12, 8, v212
	v_ashrrev_i32_e32 v195, 31, v194
	v_ashrrev_i32_e32 v199, 31, v198
	v_lshl_add_u64 v[196:197], v[194:195], 2, s[62:63]
	v_lshlrev_b64 v[130:131], 12, v[198:199]
	v_lshl_add_u64 v[236:237], v[196:197], 0, v[130:131]
	global_load_dwordx4 v[220:223], v[236:237], off nt
	global_load_dwordx4 v[224:227], v[236:237], off offset:16 nt
	global_load_dwordx4 v[228:231], v[236:237], off offset:512 nt
	global_load_dwordx4 v[232:235], v[236:237], off offset:528 nt
	v_or_b32_e32 v208, 16, v198
	v_or_b32_e32 v204, 32, v198
	v_or_b32_e32 v200, 48, v198
	v_ashrrev_i32_e32 v209, 31, v208
	v_ashrrev_i32_e32 v205, 31, v204
	v_ashrrev_i32_e32 v201, 31, v200
	v_lshlrev_b64 v[130:131], 12, v[208:209]
	v_lshlrev_b64 v[132:133], 12, v[204:205]
	v_lshlrev_b64 v[134:135], 12, v[200:201]
	v_lshl_add_u64 v[210:211], v[196:197], 0, v[130:131]
	v_lshl_add_u64 v[206:207], v[196:197], 0, v[132:133]
	v_lshl_add_u64 v[202:203], v[196:197], 0, v[134:135]
	global_load_dwordx4 v[170:173], v[210:211], off offset:16 nt
	global_load_dwordx4 v[174:177], v[210:211], off nt
	global_load_dwordx4 v[162:165], v[210:211], off offset:528 nt
	global_load_dwordx4 v[166:169], v[210:211], off offset:512 nt
	global_load_dwordx4 v[154:157], v[206:207], off offset:16 nt
	global_load_dwordx4 v[158:161], v[206:207], off nt
	global_load_dwordx4 v[146:149], v[206:207], off offset:528 nt
	global_load_dwordx4 v[150:153], v[206:207], off offset:512 nt
	global_load_dwordx4 v[138:141], v[202:203], off offset:16 nt
	global_load_dwordx4 v[142:145], v[202:203], off nt
	global_load_dwordx4 v[130:133], v[202:203], off offset:528 nt
	global_load_dwordx4 v[134:137], v[202:203], off offset:512 nt
	v_and_b32_e32 v238, 64, v216
	v_xor_b32_e32 v219, 16, v216
	v_add_u32_e32 v241, 64, v238
	v_cmp_lt_i32_e32 vcc, v219, v241
	v_lshlrev_b64 v[238:239], 10, v[198:199]
	v_xor_b32_e32 v240, 32, v216
	v_cndmask_b32_e32 v219, v216, v219, vcc
	v_lshlrev_b32_e32 v219, 2, v219
	v_lshl_add_u64 v[238:239], v[238:239], 0, v[194:195]
	v_cmp_lt_i32_e32 vcc, v240, v241
	v_lshlrev_b64 v[238:239], 1, v[238:239]
	s_lshl_b32 s22, s12, 2
	v_cndmask_b32_e32 v242, v216, v240, vcc
	v_lshl_add_u64 v[240:241], s[2:3], 0, v[238:239]
	v_or_b32_e32 v238, 0x100, v238
	s_ashr_i32 s23, s22, 31
	s_waitcnt vmcnt(0)
	v_pk_add_f32 v[128:129], v[128:129], v[222:223]
	v_pk_add_f32 v[126:127], v[126:127], v[220:221]
	v_pk_add_f32 v[120:121], v[120:121], v[230:231]
	v_pk_add_f32 v[118:119], v[118:119], v[228:229]
	v_pk_add_f32 v[124:125], v[124:125], v[226:227]
	v_pk_add_f32 v[122:123], v[122:123], v[224:225]
	v_pk_add_f32 v[114:115], v[114:115], v[232:233]
	global_store_dwordx4 v[236:237], v[126:129], off nt
	global_store_dwordx4 v[236:237], v[122:125], off offset:16 nt
	v_cvt_pk_bf16_f32 v220, v126, v127
	v_cvt_pk_bf16_f32 v221, v128, v129
	v_mul_f32_e32 v224, v119, v119
	v_mul_f32_e32 v127, v127, v127
	v_mul_f32_e32 v129, v129, v129
	v_mul_f32_e32 v225, v121, v121
	v_pk_add_f32 v[116:117], v[116:117], v[234:235]
	v_cvt_pk_bf16_f32 v222, v122, v123
	v_cvt_pk_bf16_f32 v223, v124, v125
	v_mul_f32_e32 v123, v123, v123
	v_mul_f32_e32 v125, v125, v125
	v_mul_f32_e32 v226, v115, v115
	v_fmac_f32_e32 v127, v126, v126
	v_fmac_f32_e32 v129, v128, v128
	v_fmac_f32_e32 v224, v118, v118
	v_fmac_f32_e32 v225, v120, v120
	v_mul_f32_e32 v227, v117, v117
	v_fmac_f32_e32 v123, v122, v122
	v_fmac_f32_e32 v125, v124, v124
	v_fmac_f32_e32 v226, v114, v114
	v_add_f32_e32 v122, v127, v129
	v_add_f32_e32 v124, v224, v225
	v_fmac_f32_e32 v227, v116, v116
	v_add_f32_e32 v122, v122, v123
	v_add_f32_e32 v123, v124, v226
	v_add_f32_e32 v122, v125, v122
	v_add_f32_e32 v123, v227, v123
	v_add_f32_e32 v122, v122, v123
	ds_bpermute_b32 v123, v219, v122
	global_store_dwordx4 v[240:241], v[220:223], off
	global_store_dwordx4 v[236:237], v[118:121], off offset:512 nt
	global_store_dwordx4 v[236:237], v[114:117], off offset:528 nt
	v_lshlrev_b32_e32 v128, 2, v242
	v_cvt_pk_bf16_f32 v118, v118, v119
	v_cvt_pk_bf16_f32 v119, v120, v121
	v_cvt_pk_bf16_f32 v120, v114, v115
	v_cvt_pk_bf16_f32 v121, v116, v117
	s_waitcnt lgkmcnt(0)
	v_add_f32_e32 v114, v122, v123
	ds_bpermute_b32 v115, v128, v114
	v_lshl_add_u64 v[116:117], s[2:3], 0, v[238:239]
	global_store_dwordx4 v[116:117], v[118:121], off
	s_and_saveexec_b64 s[24:25], s[4:5]
	s_cbranch_execz .LBB0_2390
	s_waitcnt lgkmcnt(0)
	v_add_f32_e32 v116, v114, v115
	v_lshlrev_b64 v[114:115], 6, v[198:199]
	v_lshl_add_u64 v[114:115], s[8:9], 0, v[114:115]
	v_lshl_add_u64 v[114:115], s[22:23], 2, v[114:115]
	s_lshl_b32 s12, s42, 2
	v_lshl_add_u64 v[114:115], v[114:115], 0, s[12:13]
	global_store_dword v[114:115], v116, off

.LBB0_2471:
	ds_read_b128 v[130:133], v213
	ds_read_b128 v[134:137], v213 offset:1024
	ds_read_b128 v[138:141], v213 offset:2048
	ds_read_b128 v[142:145], v213 offset:3072
	ds_read_b128 v[146:149], v214
	ds_read_b128 v[150:153], v214 offset:1024
	ds_read_b128 v[154:157], v214 offset:2048
	ds_read_b128 v[158:161], v214 offset:3072
	s_add_u32 s20, s18, 0xfff50080
	s_addc_u32 s21, s19, -1
	s_cmp_eq_u32 s51, 40
	s_cselect_b32 s23, s9, s21
	s_cselect_b32 s22, s8, s20
	s_cselect_b32 s21, s11, s50
	s_cselect_b32 s20, s10, s49
	v_lshl_add_u64 v[210:211], s[18:19], 0, v[186:187]
	s_add_i32 m0, s31, 0xc000
	ds_read_b128 v[162:165], v215
	ds_read_b128 v[166:169], v215 offset:1024
	ds_read_b128 v[170:173], v215 offset:2048
	ds_read_b128 v[174:177], v215 offset:3072
	ds_read_b128 v[194:197], v215 offset:4096
	ds_read_b128 v[198:201], v215 offset:5120
	ds_read_b128 v[202:205], v215 offset:6144
	ds_read_b128 v[206:209], v215 offset:7168
	global_load_lds_dwordx4 v[210:211], off
	v_lshl_add_u64 v[210:211], s[18:19], 0, v[188:189]
	s_add_i32 m0, s31, 0xe000
	s_nop 0
	global_load_lds_dwordx4 v[210:211], off
	s_waitcnt vmcnt(8)
	s_waitcnt lgkmcnt(0)
	s_barrier
	s_setprio 1
	v_mfma_f32_16x16x32_bf16 v[126:129], v[130:133], v[162:165], v[126:129]
	v_mfma_f32_16x16x32_bf16 v[122:125], v[138:141], v[162:165], v[122:125]
	v_mfma_f32_16x16x32_bf16 v[110:113], v[130:133], v[170:173], v[110:113]
	v_mfma_f32_16x16x32_bf16 v[106:109], v[138:141], v[170:173], v[106:109]
	v_mfma_f32_16x16x32_bf16 v[94:97], v[130:133], v[194:197], v[94:97]
	v_mfma_f32_16x16x32_bf16 v[90:93], v[138:141], v[194:197], v[90:93]
	v_mfma_f32_16x16x32_bf16 v[78:81], v[130:133], v[202:205], v[78:81]
	v_mfma_f32_16x16x32_bf16 v[74:77], v[138:141], v[202:205], v[74:77]
	v_mfma_f32_16x16x32_bf16 v[126:129], v[134:137], v[166:169], v[126:129]
	v_mfma_f32_16x16x32_bf16 v[122:125], v[142:145], v[166:169], v[122:125]
	v_mfma_f32_16x16x32_bf16 v[110:113], v[134:137], v[174:177], v[110:113]
	v_mfma_f32_16x16x32_bf16 v[106:109], v[142:145], v[174:177], v[106:109]
	v_mfma_f32_16x16x32_bf16 v[94:97], v[134:137], v[198:201], v[94:97]
	v_mfma_f32_16x16x32_bf16 v[90:93], v[142:145], v[198:201], v[90:93]
	v_mfma_f32_16x16x32_bf16 v[78:81], v[134:137], v[206:209], v[78:81]
	v_mfma_f32_16x16x32_bf16 v[74:77], v[142:145], v[206:209], v[74:77]
	v_mfma_f32_16x16x32_bf16 v[118:121], v[146:149], v[162:165], v[118:121]
	v_mfma_f32_16x16x32_bf16 v[114:117], v[154:157], v[162:165], v[114:117]
	v_mfma_f32_16x16x32_bf16 v[102:105], v[146:149], v[170:173], v[102:105]
	v_mfma_f32_16x16x32_bf16 v[98:101], v[154:157], v[170:173], v[98:101]
	v_mfma_f32_16x16x32_bf16 v[86:89], v[146:149], v[194:197], v[86:89]
	v_mfma_f32_16x16x32_bf16 v[82:85], v[154:157], v[194:197], v[82:85]
	v_mfma_f32_16x16x32_bf16 v[70:73], v[146:149], v[202:205], v[70:73]
	v_mfma_f32_16x16x32_bf16 v[66:69], v[154:157], v[202:205], v[66:69]
	v_mfma_f32_16x16x32_bf16 v[118:121], v[150:153], v[166:169], v[118:121]
	v_mfma_f32_16x16x32_bf16 v[114:117], v[158:161], v[166:169], v[114:117]
	v_mfma_f32_16x16x32_bf16 v[102:105], v[150:153], v[174:177], v[102:105]
	v_mfma_f32_16x16x32_bf16 v[98:101], v[158:161], v[174:177], v[98:101]
	v_mfma_f32_16x16x32_bf16 v[86:89], v[150:153], v[198:201], v[86:89]
	v_mfma_f32_16x16x32_bf16 v[82:85], v[158:161], v[198:201], v[82:85]
	v_mfma_f32_16x16x32_bf16 v[70:73], v[150:153], v[206:209], v[70:73]
	v_mfma_f32_16x16x32_bf16 v[66:69], v[158:161], v[206:209], v[66:69]
	s_setprio 0
	s_barrier
	s_add_i32 s52, s41, s30
	v_lshl_add_u64 v[210:211], s[20:21], 0, v[180:181]
	s_mov_b32 m0, s52
	ds_read_b128 v[162:165], v215 offset:16384
	ds_read_b128 v[166:169], v215 offset:17408
	ds_read_b128 v[170:173], v215 offset:18432
	ds_read_b128 v[174:177], v215 offset:19456
	ds_read_b128 v[194:197], v215 offset:20480
	ds_read_b128 v[198:201], v215 offset:21504
	ds_read_b128 v[202:205], v215 offset:22528
	ds_read_b128 v[206:209], v215 offset:23552
	global_load_lds_dwordx4 v[210:211], off
	s_add_i32 m0, s52, 0x2000
	s_add_u32 s52, s20, 0xb0000
	v_lshl_add_u64 v[220:221], s[20:21], 0, v[184:185]
	s_addc_u32 s53, s21, 0
	s_add_i32 s54, s42, s30
	global_load_lds_dwordx4 v[220:221], off
	v_lshl_add_u64 v[222:223], s[52:53], 0, v[180:181]
	s_mov_b32 m0, s54
	v_lshl_add_u64 v[224:225], s[22:23], 0, v[182:183]
	global_load_lds_dwordx4 v[222:223], off
	v_lshl_add_u64 v[222:223], s[52:53], 0, v[184:185]
	s_add_i32 m0, s54, 0x2000
	s_nop 0
	global_load_lds_dwordx4 v[222:223], off
	s_waitcnt vmcnt(6)
	s_waitcnt lgkmcnt(0)
	s_barrier
	s_setprio 1
	v_mfma_f32_16x16x32_bf16 v[62:65], v[130:133], v[162:165], v[62:65]
	v_mfma_f32_16x16x32_bf16 v[58:61], v[138:141], v[162:165], v[58:61]
	v_mfma_f32_16x16x32_bf16 v[46:49], v[130:133], v[170:173], v[46:49]
	v_mfma_f32_16x16x32_bf16 v[42:45], v[138:141], v[170:173], v[42:45]
	v_lshl_add_u64 v[222:223], s[22:23], 0, v[178:179]
	s_mov_b32 m0, s31
	s_nop 0
	global_load_lds_dwordx4 v[222:223], off
	v_mfma_f32_16x16x32_bf16 v[30:33], v[130:133], v[194:197], v[30:33]
	v_mfma_f32_16x16x32_bf16 v[26:29], v[138:141], v[194:197], v[26:29]
	v_mfma_f32_16x16x32_bf16 v[14:17], v[130:133], v[202:205], v[14:17]
	v_mfma_f32_16x16x32_bf16 v[10:13], v[138:141], v[202:205], v[10:13]
	v_mfma_f32_16x16x32_bf16 v[62:65], v[134:137], v[166:169], v[62:65]
	v_mfma_f32_16x16x32_bf16 v[58:61], v[142:145], v[166:169], v[58:61]
	v_mfma_f32_16x16x32_bf16 v[46:49], v[134:137], v[174:177], v[46:49]
	v_mfma_f32_16x16x32_bf16 v[42:45], v[142:145], v[174:177], v[42:45]
	s_mov_b32 m0, s33
	s_nop 0
	global_load_lds_dwordx4 v[224:225], off
	v_mfma_f32_16x16x32_bf16 v[30:33], v[134:137], v[198:201], v[30:33]
	v_mfma_f32_16x16x32_bf16 v[26:29], v[142:145], v[198:201], v[26:29]
	v_mfma_f32_16x16x32_bf16 v[14:17], v[134:137], v[206:209], v[14:17]
	v_mfma_f32_16x16x32_bf16 v[10:13], v[142:145], v[206:209], v[10:13]
	v_mfma_f32_16x16x32_bf16 v[54:57], v[146:149], v[162:165], v[54:57]
	v_mfma_f32_16x16x32_bf16 v[50:53], v[154:157], v[162:165], v[50:53]
	v_mfma_f32_16x16x32_bf16 v[38:41], v[146:149], v[170:173], v[38:41]
	v_mfma_f32_16x16x32_bf16 v[34:37], v[154:157], v[170:173], v[34:37]
	v_mfma_f32_16x16x32_bf16 v[22:25], v[146:149], v[194:197], v[22:25]
	v_mfma_f32_16x16x32_bf16 v[18:21], v[154:157], v[194:197], v[18:21]
	v_mfma_f32_16x16x32_bf16 v[6:9], v[146:149], v[202:205], v[6:9]
	v_mfma_f32_16x16x32_bf16 v[2:5], v[154:157], v[202:205], v[2:5]
	v_mfma_f32_16x16x32_bf16 v[54:57], v[150:153], v[166:169], v[54:57]
	v_mfma_f32_16x16x32_bf16 v[50:53], v[158:161], v[166:169], v[50:53]
	v_mfma_f32_16x16x32_bf16 v[38:41], v[150:153], v[174:177], v[38:41]
	v_mfma_f32_16x16x32_bf16 v[34:37], v[158:161], v[174:177], v[34:37]
	v_mfma_f32_16x16x32_bf16 v[22:25], v[150:153], v[198:201], v[22:25]
	v_mfma_f32_16x16x32_bf16 v[18:21], v[158:161], v[198:201], v[18:21]
	v_mfma_f32_16x16x32_bf16 v[6:9], v[150:153], v[206:209], v[6:9]
	v_mfma_f32_16x16x32_bf16 v[2:5], v[158:161], v[206:209], v[2:5]
	s_setprio 0
	s_barrier
	ds_read_b128 v[130:133], v217
	ds_read_b128 v[134:137], v217 offset:1024
	ds_read_b128 v[138:141], v217 offset:2048
	ds_read_b128 v[142:145], v217 offset:3072
	ds_read_b128 v[146:149], v218
	ds_read_b128 v[150:153], v218 offset:1024
	ds_read_b128 v[154:157], v218 offset:2048
	ds_read_b128 v[158:161], v218 offset:3072
	s_add_u32 s22, s22, 0xb0000
	s_addc_u32 s23, s23, 0
	s_mov_b32 m0, s34
	v_lshl_add_u64 v[226:227], s[22:23], 0, v[178:179]
	ds_read_b128 v[162:165], v215 offset:32768
	ds_read_b128 v[166:169], v215 offset:33792
	ds_read_b128 v[170:173], v215 offset:34816
	ds_read_b128 v[174:177], v215 offset:35840
	ds_read_b128 v[194:197], v215 offset:36864
	ds_read_b128 v[198:201], v215 offset:37888
	ds_read_b128 v[202:205], v215 offset:38912
	ds_read_b128 v[206:209], v215 offset:39936
	global_load_lds_dwordx4 v[226:227], off
	v_lshl_add_u64 v[226:227], s[22:23], 0, v[182:183]
	s_mov_b32 m0, s35
	s_nop 0
	global_load_lds_dwordx4 v[226:227], off
	s_waitcnt vmcnt(8)
	s_waitcnt lgkmcnt(0)
	s_barrier
	s_setprio 1
	v_mfma_f32_16x16x32_bf16 v[126:129], v[130:133], v[162:165], v[126:129]
	v_mfma_f32_16x16x32_bf16 v[122:125], v[138:141], v[162:165], v[122:125]
	v_mfma_f32_16x16x32_bf16 v[110:113], v[130:133], v[170:173], v[110:113]
	v_mfma_f32_16x16x32_bf16 v[106:109], v[138:141], v[170:173], v[106:109]
	v_mfma_f32_16x16x32_bf16 v[94:97], v[130:133], v[194:197], v[94:97]
	v_mfma_f32_16x16x32_bf16 v[90:93], v[138:141], v[194:197], v[90:93]
	v_mfma_f32_16x16x32_bf16 v[78:81], v[130:133], v[202:205], v[78:81]
	v_mfma_f32_16x16x32_bf16 v[74:77], v[138:141], v[202:205], v[74:77]
	v_mfma_f32_16x16x32_bf16 v[126:129], v[134:137], v[166:169], v[126:129]
	v_mfma_f32_16x16x32_bf16 v[122:125], v[142:145], v[166:169], v[122:125]
	v_mfma_f32_16x16x32_bf16 v[110:113], v[134:137], v[174:177], v[110:113]
	v_mfma_f32_16x16x32_bf16 v[106:109], v[142:145], v[174:177], v[106:109]
	v_mfma_f32_16x16x32_bf16 v[94:97], v[134:137], v[198:201], v[94:97]
	v_mfma_f32_16x16x32_bf16 v[90:93], v[142:145], v[198:201], v[90:93]
	v_mfma_f32_16x16x32_bf16 v[78:81], v[134:137], v[206:209], v[78:81]
	v_mfma_f32_16x16x32_bf16 v[74:77], v[142:145], v[206:209], v[74:77]
	v_mfma_f32_16x16x32_bf16 v[118:121], v[146:149], v[162:165], v[118:121]
	v_mfma_f32_16x16x32_bf16 v[114:117], v[154:157], v[162:165], v[114:117]
	v_mfma_f32_16x16x32_bf16 v[102:105], v[146:149], v[170:173], v[102:105]
	v_mfma_f32_16x16x32_bf16 v[98:101], v[154:157], v[170:173], v[98:101]
	v_mfma_f32_16x16x32_bf16 v[86:89], v[146:149], v[194:197], v[86:89]
	v_mfma_f32_16x16x32_bf16 v[82:85], v[154:157], v[194:197], v[82:85]
	v_mfma_f32_16x16x32_bf16 v[70:73], v[146:149], v[202:205], v[70:73]
	v_mfma_f32_16x16x32_bf16 v[66:69], v[154:157], v[202:205], v[66:69]
	v_mfma_f32_16x16x32_bf16 v[118:121], v[150:153], v[166:169], v[118:121]
	v_mfma_f32_16x16x32_bf16 v[114:117], v[158:161], v[166:169], v[114:117]
	v_mfma_f32_16x16x32_bf16 v[102:105], v[150:153], v[174:177], v[102:105]
	v_mfma_f32_16x16x32_bf16 v[98:101], v[158:161], v[174:177], v[98:101]
	v_mfma_f32_16x16x32_bf16 v[86:89], v[150:153], v[198:201], v[86:89]
	v_mfma_f32_16x16x32_bf16 v[82:85], v[158:161], v[198:201], v[82:85]
	v_mfma_f32_16x16x32_bf16 v[70:73], v[150:153], v[206:209], v[70:73]
	v_mfma_f32_16x16x32_bf16 v[66:69], v[158:161], v[206:209], v[66:69]
	s_setprio 0
	s_barrier
	s_add_i32 s22, s43, s30
	v_lshl_add_u64 v[210:211], v[210:211], 0, s[14:15]
	s_mov_b32 m0, s22
	ds_read_b128 v[162:165], v215 offset:49152
	ds_read_b128 v[166:169], v215 offset:50176
	ds_read_b128 v[170:173], v215 offset:51200
	ds_read_b128 v[174:177], v215 offset:52224
	ds_read_b128 v[194:197], v215 offset:53248
	ds_read_b128 v[198:201], v215 offset:54272
	ds_read_b128 v[202:205], v215 offset:55296
	ds_read_b128 v[206:209], v215 offset:56320
	global_load_lds_dwordx4 v[210:211], off
	s_add_i32 m0, s22, 0x2000
	s_add_u32 s20, s20, 0xb0080
	v_lshl_add_u64 v[210:211], v[220:221], 0, s[14:15]
	s_addc_u32 s21, s21, 0
	s_add_i32 s22, s44, s30
	global_load_lds_dwordx4 v[210:211], off
	v_lshl_add_u64 v[210:211], s[20:21], 0, v[180:181]
	s_mov_b32 m0, s22
	s_nop 0
	global_load_lds_dwordx4 v[210:211], off
	v_lshl_add_u64 v[210:211], s[20:21], 0, v[184:185]
	s_add_i32 m0, s22, 0x2000
	s_nop 0
	global_load_lds_dwordx4 v[210:211], off
	s_waitcnt vmcnt(6)
	s_waitcnt lgkmcnt(0)
	s_barrier
	s_setprio 1
	v_mfma_f32_16x16x32_bf16 v[62:65], v[130:133], v[162:165], v[62:65]
	v_mfma_f32_16x16x32_bf16 v[58:61], v[138:141], v[162:165], v[58:61]
	v_mfma_f32_16x16x32_bf16 v[46:49], v[130:133], v[170:173], v[46:49]
	v_mfma_f32_16x16x32_bf16 v[42:45], v[138:141], v[170:173], v[42:45]
	v_lshl_add_u64 v[210:211], v[222:223], 0, s[14:15]
	s_mov_b32 m0, s37
	s_nop 0
	global_load_lds_dwordx4 v[210:211], off
	v_mfma_f32_16x16x32_bf16 v[30:33], v[130:133], v[194:197], v[30:33]
	v_mfma_f32_16x16x32_bf16 v[26:29], v[138:141], v[194:197], v[26:29]
	v_mfma_f32_16x16x32_bf16 v[14:17], v[130:133], v[202:205], v[14:17]
	v_mfma_f32_16x16x32_bf16 v[10:13], v[138:141], v[202:205], v[10:13]
	v_mfma_f32_16x16x32_bf16 v[62:65], v[134:137], v[166:169], v[62:65]
	v_mfma_f32_16x16x32_bf16 v[58:61], v[142:145], v[166:169], v[58:61]
	v_mfma_f32_16x16x32_bf16 v[46:49], v[134:137], v[174:177], v[46:49]
	v_mfma_f32_16x16x32_bf16 v[42:45], v[142:145], v[174:177], v[42:45]
	v_lshl_add_u64 v[210:211], v[224:225], 0, s[14:15]
	s_mov_b32 m0, s38
	s_nop 0
	global_load_lds_dwordx4 v[210:211], off
	v_mfma_f32_16x16x32_bf16 v[30:33], v[134:137], v[198:201], v[30:33]
	v_mfma_f32_16x16x32_bf16 v[26:29], v[142:145], v[198:201], v[26:29]
	v_mfma_f32_16x16x32_bf16 v[14:17], v[134:137], v[206:209], v[14:17]
	v_mfma_f32_16x16x32_bf16 v[10:13], v[142:145], v[206:209], v[10:13]
	v_mfma_f32_16x16x32_bf16 v[54:57], v[146:149], v[162:165], v[54:57]
	v_mfma_f32_16x16x32_bf16 v[50:53], v[154:157], v[162:165], v[50:53]
	v_mfma_f32_16x16x32_bf16 v[38:41], v[146:149], v[170:173], v[38:41]
	v_mfma_f32_16x16x32_bf16 v[34:37], v[154:157], v[170:173], v[34:37]
	v_mfma_f32_16x16x32_bf16 v[22:25], v[146:149], v[194:197], v[22:25]
	v_mfma_f32_16x16x32_bf16 v[18:21], v[154:157], v[194:197], v[18:21]
	v_mfma_f32_16x16x32_bf16 v[6:9], v[146:149], v[202:205], v[6:9]
	v_mfma_f32_16x16x32_bf16 v[2:5], v[154:157], v[202:205], v[2:5]
	v_mfma_f32_16x16x32_bf16 v[54:57], v[150:153], v[166:169], v[54:57]
	v_mfma_f32_16x16x32_bf16 v[50:53], v[158:161], v[166:169], v[50:53]
	v_mfma_f32_16x16x32_bf16 v[38:41], v[150:153], v[174:177], v[38:41]
	v_mfma_f32_16x16x32_bf16 v[34:37], v[158:161], v[174:177], v[34:37]
	v_mfma_f32_16x16x32_bf16 v[22:25], v[150:153], v[198:201], v[22:25]
	v_mfma_f32_16x16x32_bf16 v[18:21], v[158:161], v[198:201], v[18:21]
	v_mfma_f32_16x16x32_bf16 v[6:9], v[150:153], v[206:209], v[6:9]
	v_mfma_f32_16x16x32_bf16 v[2:5], v[158:161], v[206:209], v[2:5]
	s_setprio 0
	s_barrier
	s_add_i32 s51, s51, 2
	s_add_u32 s18, s18, 0x100
	s_addc_u32 s19, s19, 0
	s_add_u32 s49, s49, 0x100
	s_addc_u32 s50, s50, 0
	s_cmp_gt_u32 s51, 41
	s_cbranch_scc0 .LBB0_2471
	v_lshl_add_u32 v198, s48, 8, v1
	v_lshl_or_b32 v194, s16, 8, v212
	v_ashrrev_i32_e32 v195, 31, v194
	v_ashrrev_i32_e32 v199, 31, v198
	v_lshl_add_u64 v[196:197], v[194:195], 2, s[62:63]
	v_lshlrev_b64 v[130:131], 12, v[198:199]
	v_lshl_add_u64 v[236:237], v[196:197], 0, v[130:131]
	global_load_dwordx4 v[220:223], v[236:237], off nt
	global_load_dwordx4 v[224:227], v[236:237], off offset:16 nt
	global_load_dwordx4 v[228:231], v[236:237], off offset:512 nt
	global_load_dwordx4 v[232:235], v[236:237], off offset:528 nt
	v_or_b32_e32 v208, 16, v198
	v_or_b32_e32 v204, 32, v198
	v_or_b32_e32 v200, 48, v198
	v_ashrrev_i32_e32 v209, 31, v208
	v_ashrrev_i32_e32 v205, 31, v204
	v_ashrrev_i32_e32 v201, 31, v200
	v_lshlrev_b64 v[130:131], 12, v[208:209]
	v_lshlrev_b64 v[132:133], 12, v[204:205]
	v_lshlrev_b64 v[134:135], 12, v[200:201]
	v_lshl_add_u64 v[210:211], v[196:197], 0, v[130:131]
	v_lshl_add_u64 v[206:207], v[196:197], 0, v[132:133]
	v_lshl_add_u64 v[202:203], v[196:197], 0, v[134:135]
	global_load_dwordx4 v[170:173], v[210:211], off offset:16 nt
	global_load_dwordx4 v[174:177], v[210:211], off nt
	global_load_dwordx4 v[162:165], v[210:211], off offset:528 nt
	global_load_dwordx4 v[166:169], v[210:211], off offset:512 nt
	global_load_dwordx4 v[154:157], v[206:207], off offset:16 nt
	global_load_dwordx4 v[158:161], v[206:207], off nt
	global_load_dwordx4 v[146:149], v[206:207], off offset:528 nt
	global_load_dwordx4 v[150:153], v[206:207], off offset:512 nt
	global_load_dwordx4 v[138:141], v[202:203], off offset:16 nt
	global_load_dwordx4 v[142:145], v[202:203], off nt
	global_load_dwordx4 v[130:133], v[202:203], off offset:528 nt
	global_load_dwordx4 v[134:137], v[202:203], off offset:512 nt
	v_and_b32_e32 v238, 64, v216
	v_xor_b32_e32 v219, 16, v216
	v_add_u32_e32 v241, 64, v238
	v_cmp_lt_i32_e32 vcc, v219, v241
	v_lshlrev_b64 v[238:239], 10, v[198:199]
	v_xor_b32_e32 v240, 32, v216
	v_cndmask_b32_e32 v219, v216, v219, vcc
	v_lshlrev_b32_e32 v219, 2, v219
	v_lshl_add_u64 v[238:239], v[238:239], 0, v[194:195]
	v_cmp_lt_i32_e32 vcc, v240, v241
	v_lshlrev_b64 v[238:239], 1, v[238:239]
	s_lshl_b32 s18, s16, 2
	v_cndmask_b32_e32 v242, v216, v240, vcc
	v_lshl_add_u64 v[240:241], s[2:3], 0, v[238:239]
	v_or_b32_e32 v238, 0x100, v238
	s_ashr_i32 s19, s18, 31
	s_waitcnt vmcnt(0)
	v_pk_fma_f32 v[128:129], v[128:129], 0.5, v[222:223] op_sel_hi:[1,0,1]
	v_pk_fma_f32 v[126:127], v[126:127], 0.5, v[220:221] op_sel_hi:[1,0,1]
	v_pk_fma_f32 v[120:121], v[120:121], 0.5, v[230:231] op_sel_hi:[1,0,1]
	v_pk_fma_f32 v[118:119], v[118:119], 0.5, v[228:229] op_sel_hi:[1,0,1]
	v_pk_fma_f32 v[124:125], v[124:125], 0.5, v[226:227] op_sel_hi:[1,0,1]
	v_pk_fma_f32 v[122:123], v[122:123], 0.5, v[224:225] op_sel_hi:[1,0,1]
	v_pk_fma_f32 v[114:115], v[114:115], 0.5, v[232:233] op_sel_hi:[1,0,1]
	global_store_dwordx4 v[236:237], v[126:129], off nt
	global_store_dwordx4 v[236:237], v[122:125], off offset:16 nt
	v_cvt_pk_bf16_f32 v220, v126, v127
	v_cvt_pk_bf16_f32 v221, v128, v129
	v_mul_f32_e32 v224, v119, v119
	v_mul_f32_e32 v127, v127, v127
	v_mul_f32_e32 v129, v129, v129
	v_mul_f32_e32 v225, v121, v121
	v_pk_fma_f32 v[116:117], v[116:117], 0.5, v[234:235] op_sel_hi:[1,0,1]
	v_cvt_pk_bf16_f32 v222, v122, v123
	v_cvt_pk_bf16_f32 v223, v124, v125
	v_mul_f32_e32 v123, v123, v123
	v_mul_f32_e32 v125, v125, v125
	v_mul_f32_e32 v226, v115, v115
	v_fmac_f32_e32 v127, v126, v126
	v_fmac_f32_e32 v129, v128, v128
	v_fmac_f32_e32 v224, v118, v118
	v_fmac_f32_e32 v225, v120, v120
	v_mul_f32_e32 v227, v117, v117
	v_fmac_f32_e32 v123, v122, v122
	v_fmac_f32_e32 v125, v124, v124
	v_fmac_f32_e32 v226, v114, v114
	v_add_f32_e32 v122, v127, v129
	v_add_f32_e32 v124, v224, v225
	v_fmac_f32_e32 v227, v116, v116
	v_add_f32_e32 v122, v122, v123
	v_add_f32_e32 v123, v124, v226
	v_add_f32_e32 v122, v125, v122
	v_add_f32_e32 v123, v227, v123
	v_add_f32_e32 v122, v122, v123
	ds_bpermute_b32 v123, v219, v122
	global_store_dwordx4 v[240:241], v[220:223], off
	global_store_dwordx4 v[236:237], v[118:121], off offset:512 nt
	global_store_dwordx4 v[236:237], v[114:117], off offset:528 nt
	v_lshlrev_b32_e32 v128, 2, v242
	v_cvt_pk_bf16_f32 v118, v118, v119
	v_cvt_pk_bf16_f32 v119, v120, v121
	v_cvt_pk_bf16_f32 v120, v114, v115
	v_cvt_pk_bf16_f32 v121, v116, v117
	s_waitcnt lgkmcnt(0)
	v_add_f32_e32 v114, v122, v123
	ds_bpermute_b32 v115, v128, v114
	v_lshl_add_u64 v[116:117], s[2:3], 0, v[238:239]
	global_store_dwordx4 v[116:117], v[118:121], off
	s_and_saveexec_b64 s[20:21], s[4:5]
	s_cbranch_execz .LBB0_2474
	s_waitcnt lgkmcnt(0)
	v_add_f32_e32 v116, v114, v115
	v_lshlrev_b64 v[114:115], 6, v[198:199]
	v_lshl_add_u64 v[114:115], s[12:13], 0, v[114:115]
	v_lshl_add_u64 v[114:115], s[18:19], 2, v[114:115]
	s_lshl_b32 s16, s36, 2
	v_lshl_add_u64 v[114:115], v[114:115], 0, s[16:17]
	global_store_dword v[114:115], v116, off

.LBB0_2599:
	ds_read_b128 v[82:85], v165
	ds_read_b128 v[86:89], v165 offset:1024
	ds_read_b128 v[90:93], v165 offset:2048
	ds_read_b128 v[94:97], v165 offset:3072
	ds_read_b128 v[146:149], v184
	ds_read_b128 v[150:153], v184 offset:1024
	ds_read_b128 v[180:183], v184 offset:2048
	ds_read_b128 v[194:197], v184 offset:3072
	s_add_u32 s12, s10, 0xfffc0080
	s_addc_u32 s13, s11, -1
	s_cmp_eq_u32 s84, 12
	s_cselect_b32 s15, s1, s13
	s_cselect_b32 s14, s3, s12
	s_cselect_b32 s13, s16, s45
	s_cselect_b32 s12, s17, s43
	v_lshl_add_u64 v[230:231], s[10:11], 0, v[170:171]
	s_add_i32 m0, s54, 0xc000
	ds_read_b128 v[198:201], v185
	ds_read_b128 v[202:205], v185 offset:1024
	ds_read_b128 v[206:209], v185 offset:2048
	ds_read_b128 v[210:213], v185 offset:3072
	ds_read_b128 v[214:217], v185 offset:4096
	ds_read_b128 v[218:221], v185 offset:5120
	ds_read_b128 v[222:225], v185 offset:6144
	ds_read_b128 v[226:229], v185 offset:7168
	global_load_lds_dwordx4 v[230:231], off
	v_lshl_add_u64 v[230:231], s[10:11], 0, v[172:173]
	s_add_i32 m0, s54, 0xe000
	s_nop 0
	global_load_lds_dwordx4 v[230:231], off
	s_waitcnt vmcnt(8)
	s_waitcnt lgkmcnt(0)
	s_barrier
	s_setprio 1
	v_mfma_f32_16x16x32_bf16 v[62:65], v[82:85], v[198:201], v[62:65]
	v_mfma_f32_16x16x32_bf16 v[58:61], v[90:93], v[198:201], v[58:61]
	v_mfma_f32_16x16x32_bf16 v[54:57], v[82:85], v[206:209], v[54:57]
	v_mfma_f32_16x16x32_bf16 v[50:53], v[90:93], v[206:209], v[50:53]
	v_mfma_f32_16x16x32_bf16 v[46:49], v[82:85], v[214:217], v[46:49]
	v_mfma_f32_16x16x32_bf16 v[42:45], v[90:93], v[214:217], v[42:45]
	v_mfma_f32_16x16x32_bf16 v[38:41], v[82:85], v[222:225], v[38:41]
	v_mfma_f32_16x16x32_bf16 v[34:37], v[90:93], v[222:225], v[34:37]
	v_mfma_f32_16x16x32_bf16 v[62:65], v[86:89], v[202:205], v[62:65]
	v_mfma_f32_16x16x32_bf16 v[58:61], v[94:97], v[202:205], v[58:61]
	v_mfma_f32_16x16x32_bf16 v[54:57], v[86:89], v[210:213], v[54:57]
	v_mfma_f32_16x16x32_bf16 v[50:53], v[94:97], v[210:213], v[50:53]
	v_mfma_f32_16x16x32_bf16 v[46:49], v[86:89], v[218:221], v[46:49]
	v_mfma_f32_16x16x32_bf16 v[42:45], v[94:97], v[218:221], v[42:45]
	v_mfma_f32_16x16x32_bf16 v[38:41], v[86:89], v[226:229], v[38:41]
	v_mfma_f32_16x16x32_bf16 v[34:37], v[94:97], v[226:229], v[34:37]
	v_mfma_f32_16x16x32_bf16 v[142:145], v[146:149], v[198:201], v[142:145]
	v_mfma_f32_16x16x32_bf16 v[138:141], v[180:183], v[198:201], v[138:141]
	v_mfma_f32_16x16x32_bf16 v[134:137], v[146:149], v[206:209], v[134:137]
	v_mfma_f32_16x16x32_bf16 v[130:133], v[180:183], v[206:209], v[130:133]
	v_mfma_f32_16x16x32_bf16 v[126:129], v[146:149], v[214:217], v[126:129]
	v_mfma_f32_16x16x32_bf16 v[122:125], v[180:183], v[214:217], v[122:125]
	v_mfma_f32_16x16x32_bf16 v[118:121], v[146:149], v[222:225], v[118:121]
	v_mfma_f32_16x16x32_bf16 v[114:117], v[180:183], v[222:225], v[114:117]
	v_mfma_f32_16x16x32_bf16 v[142:145], v[150:153], v[202:205], v[142:145]
	v_mfma_f32_16x16x32_bf16 v[138:141], v[194:197], v[202:205], v[138:141]
	v_mfma_f32_16x16x32_bf16 v[134:137], v[150:153], v[210:213], v[134:137]
	v_mfma_f32_16x16x32_bf16 v[130:133], v[194:197], v[210:213], v[130:133]
	v_mfma_f32_16x16x32_bf16 v[126:129], v[150:153], v[218:221], v[126:129]
	v_mfma_f32_16x16x32_bf16 v[122:125], v[194:197], v[218:221], v[122:125]
	v_mfma_f32_16x16x32_bf16 v[118:121], v[150:153], v[226:229], v[118:121]
	v_mfma_f32_16x16x32_bf16 v[114:117], v[194:197], v[226:229], v[114:117]
	s_setprio 0
	s_barrier
	s_add_i32 s85, s68, s53
	v_lshl_add_u64 v[230:231], s[12:13], 0, v[156:157]
	s_mov_b32 m0, s85
	ds_read_b128 v[198:201], v185 offset:16384
	ds_read_b128 v[202:205], v185 offset:17408
	ds_read_b128 v[206:209], v185 offset:18432
	ds_read_b128 v[210:213], v185 offset:19456
	ds_read_b128 v[214:217], v185 offset:20480
	ds_read_b128 v[218:221], v185 offset:21504
	ds_read_b128 v[222:225], v185 offset:22528
	ds_read_b128 v[226:229], v185 offset:23552
	global_load_lds_dwordx4 v[230:231], off
	s_add_i32 m0, s85, 0x2000
	s_add_u32 s86, s12, 0x40000
	v_lshl_add_u64 v[232:233], s[12:13], 0, v[160:161]
	s_addc_u32 s87, s13, 0
	s_add_i32 s85, s69, s53
	global_load_lds_dwordx4 v[232:233], off
	v_lshl_add_u64 v[234:235], s[86:87], 0, v[156:157]
	s_mov_b32 m0, s85
	v_lshl_add_u64 v[236:237], s[14:15], 0, v[158:159]
	global_load_lds_dwordx4 v[234:235], off
	v_lshl_add_u64 v[234:235], s[86:87], 0, v[160:161]
	s_add_i32 m0, s85, 0x2000
	s_nop 0
	global_load_lds_dwordx4 v[234:235], off
	s_waitcnt vmcnt(6)
	s_waitcnt lgkmcnt(0)
	s_barrier
	s_setprio 1
	v_mfma_f32_16x16x32_bf16 v[30:33], v[82:85], v[198:201], v[30:33]
	v_mfma_f32_16x16x32_bf16 v[26:29], v[90:93], v[198:201], v[26:29]
	v_mfma_f32_16x16x32_bf16 v[22:25], v[82:85], v[206:209], v[22:25]
	v_mfma_f32_16x16x32_bf16 v[18:21], v[90:93], v[206:209], v[18:21]
	v_lshl_add_u64 v[234:235], s[14:15], 0, v[154:155]
	s_mov_b32 m0, s54
	s_nop 0
	global_load_lds_dwordx4 v[234:235], off
	v_mfma_f32_16x16x32_bf16 v[14:17], v[82:85], v[214:217], v[14:17]
	v_mfma_f32_16x16x32_bf16 v[10:13], v[90:93], v[214:217], v[10:13]
	v_mfma_f32_16x16x32_bf16 v[6:9], v[82:85], v[222:225], v[6:9]
	v_mfma_f32_16x16x32_bf16 v[2:5], v[90:93], v[222:225], v[2:5]
	v_mfma_f32_16x16x32_bf16 v[30:33], v[86:89], v[202:205], v[30:33]
	v_mfma_f32_16x16x32_bf16 v[26:29], v[94:97], v[202:205], v[26:29]
	v_mfma_f32_16x16x32_bf16 v[22:25], v[86:89], v[210:213], v[22:25]
	v_mfma_f32_16x16x32_bf16 v[18:21], v[94:97], v[210:213], v[18:21]
	s_mov_b32 m0, s55
	s_nop 0
	global_load_lds_dwordx4 v[236:237], off
	v_mfma_f32_16x16x32_bf16 v[14:17], v[86:89], v[218:221], v[14:17]
	v_mfma_f32_16x16x32_bf16 v[10:13], v[94:97], v[218:221], v[10:13]
	v_mfma_f32_16x16x32_bf16 v[6:9], v[86:89], v[226:229], v[6:9]
	v_mfma_f32_16x16x32_bf16 v[2:5], v[94:97], v[226:229], v[2:5]
	v_mfma_f32_16x16x32_bf16 v[78:81], v[146:149], v[214:217], v[78:81]
	v_mfma_f32_16x16x32_bf16 v[74:77], v[180:183], v[214:217], v[74:77]
	v_mfma_f32_16x16x32_bf16 v[70:73], v[146:149], v[222:225], v[70:73]
	v_mfma_f32_16x16x32_bf16 v[66:69], v[180:183], v[222:225], v[66:69]
	v_mfma_f32_16x16x32_bf16 v[82:85], v[146:149], v[198:201], v[110:113]
	v_mfma_f32_16x16x32_bf16 v[86:89], v[180:183], v[198:201], v[106:109]
	v_mfma_f32_16x16x32_bf16 v[90:93], v[146:149], v[206:209], v[102:105]
	v_mfma_f32_16x16x32_bf16 v[94:97], v[180:183], v[206:209], v[98:101]
	v_mfma_f32_16x16x32_bf16 v[78:81], v[150:153], v[218:221], v[78:81]
	v_mfma_f32_16x16x32_bf16 v[74:77], v[194:197], v[218:221], v[74:77]
	v_mfma_f32_16x16x32_bf16 v[70:73], v[150:153], v[226:229], v[70:73]
	v_mfma_f32_16x16x32_bf16 v[66:69], v[194:197], v[226:229], v[66:69]
	v_mfma_f32_16x16x32_bf16 v[82:85], v[150:153], v[202:205], v[82:85]
	v_mfma_f32_16x16x32_bf16 v[86:89], v[194:197], v[202:205], v[86:89]
	v_mfma_f32_16x16x32_bf16 v[90:93], v[150:153], v[210:213], v[90:93]
	v_mfma_f32_16x16x32_bf16 v[94:97], v[194:197], v[210:213], v[94:97]
	s_setprio 0
	s_barrier
	ds_read_b128 v[98:101], v189
	ds_read_b128 v[102:105], v189 offset:1024
	ds_read_b128 v[106:109], v189 offset:2048
	ds_read_b128 v[110:113], v189 offset:3072
	ds_read_b128 v[146:149], v190
	ds_read_b128 v[150:153], v190 offset:1024
	ds_read_b128 v[180:183], v190 offset:2048
	ds_read_b128 v[194:197], v190 offset:3072
	s_add_u32 s14, s14, 0x40000
	s_addc_u32 s15, s15, 0
	s_mov_b32 m0, s56
	v_lshl_add_u64 v[238:239], s[14:15], 0, v[154:155]
	ds_read_b128 v[198:201], v185 offset:32768
	ds_read_b128 v[202:205], v185 offset:33792
	ds_read_b128 v[206:209], v185 offset:34816
	ds_read_b128 v[210:213], v185 offset:35840
	ds_read_b128 v[214:217], v185 offset:36864
	ds_read_b128 v[218:221], v185 offset:37888
	ds_read_b128 v[222:225], v185 offset:38912
	ds_read_b128 v[226:229], v185 offset:39936
	global_load_lds_dwordx4 v[238:239], off
	v_lshl_add_u64 v[238:239], s[14:15], 0, v[158:159]
	s_mov_b32 m0, s57
	s_nop 0
	global_load_lds_dwordx4 v[238:239], off
	s_waitcnt vmcnt(8)
	s_waitcnt lgkmcnt(0)
	s_barrier
	s_setprio 1
	v_mfma_f32_16x16x32_bf16 v[62:65], v[98:101], v[198:201], v[62:65]
	v_mfma_f32_16x16x32_bf16 v[58:61], v[106:109], v[198:201], v[58:61]
	v_mfma_f32_16x16x32_bf16 v[54:57], v[98:101], v[206:209], v[54:57]
	v_mfma_f32_16x16x32_bf16 v[50:53], v[106:109], v[206:209], v[50:53]
	v_mfma_f32_16x16x32_bf16 v[46:49], v[98:101], v[214:217], v[46:49]
	v_mfma_f32_16x16x32_bf16 v[42:45], v[106:109], v[214:217], v[42:45]
	v_mfma_f32_16x16x32_bf16 v[38:41], v[98:101], v[222:225], v[38:41]
	v_mfma_f32_16x16x32_bf16 v[34:37], v[106:109], v[222:225], v[34:37]
	v_mfma_f32_16x16x32_bf16 v[62:65], v[102:105], v[202:205], v[62:65]
	v_mfma_f32_16x16x32_bf16 v[58:61], v[110:113], v[202:205], v[58:61]
	v_mfma_f32_16x16x32_bf16 v[54:57], v[102:105], v[210:213], v[54:57]
	v_mfma_f32_16x16x32_bf16 v[50:53], v[110:113], v[210:213], v[50:53]
	v_mfma_f32_16x16x32_bf16 v[46:49], v[102:105], v[218:221], v[46:49]
	v_mfma_f32_16x16x32_bf16 v[42:45], v[110:113], v[218:221], v[42:45]
	v_mfma_f32_16x16x32_bf16 v[38:41], v[102:105], v[226:229], v[38:41]
	v_mfma_f32_16x16x32_bf16 v[34:37], v[110:113], v[226:229], v[34:37]
	v_mfma_f32_16x16x32_bf16 v[142:145], v[146:149], v[198:201], v[142:145]
	v_mfma_f32_16x16x32_bf16 v[138:141], v[180:183], v[198:201], v[138:141]
	v_mfma_f32_16x16x32_bf16 v[134:137], v[146:149], v[206:209], v[134:137]
	v_mfma_f32_16x16x32_bf16 v[130:133], v[180:183], v[206:209], v[130:133]
	v_mfma_f32_16x16x32_bf16 v[126:129], v[146:149], v[214:217], v[126:129]
	v_mfma_f32_16x16x32_bf16 v[122:125], v[180:183], v[214:217], v[122:125]
	v_mfma_f32_16x16x32_bf16 v[118:121], v[146:149], v[222:225], v[118:121]
	v_mfma_f32_16x16x32_bf16 v[114:117], v[180:183], v[222:225], v[114:117]
	v_mfma_f32_16x16x32_bf16 v[142:145], v[150:153], v[202:205], v[142:145]
	v_mfma_f32_16x16x32_bf16 v[138:141], v[194:197], v[202:205], v[138:141]
	v_mfma_f32_16x16x32_bf16 v[134:137], v[150:153], v[210:213], v[134:137]
	v_mfma_f32_16x16x32_bf16 v[130:133], v[194:197], v[210:213], v[130:133]
	v_mfma_f32_16x16x32_bf16 v[126:129], v[150:153], v[218:221], v[126:129]
	v_mfma_f32_16x16x32_bf16 v[122:125], v[194:197], v[218:221], v[122:125]
	v_mfma_f32_16x16x32_bf16 v[118:121], v[150:153], v[226:229], v[118:121]
	v_mfma_f32_16x16x32_bf16 v[114:117], v[194:197], v[226:229], v[114:117]
	s_setprio 0
	s_barrier
	s_add_i32 s14, s82, s53
	v_lshl_add_u64 v[230:231], v[230:231], 0, s[38:39]
	s_mov_b32 m0, s14
	ds_read_b128 v[198:201], v185 offset:49152
	ds_read_b128 v[202:205], v185 offset:50176
	ds_read_b128 v[206:209], v185 offset:51200
	ds_read_b128 v[210:213], v185 offset:52224
	ds_read_b128 v[214:217], v185 offset:53248
	ds_read_b128 v[218:221], v185 offset:54272
	ds_read_b128 v[222:225], v185 offset:55296
	ds_read_b128 v[226:229], v185 offset:56320
	global_load_lds_dwordx4 v[230:231], off
	s_add_i32 m0, s14, 0x2000
	s_add_u32 s12, s12, 0x40080
	v_lshl_add_u64 v[230:231], v[232:233], 0, s[38:39]
	s_addc_u32 s13, s13, 0
	s_add_i32 s14, s83, s53
	global_load_lds_dwordx4 v[230:231], off
	v_lshl_add_u64 v[230:231], s[12:13], 0, v[156:157]
	s_mov_b32 m0, s14
	s_nop 0
	global_load_lds_dwordx4 v[230:231], off
	v_lshl_add_u64 v[230:231], s[12:13], 0, v[160:161]
	s_add_i32 m0, s14, 0x2000
	s_nop 0
	global_load_lds_dwordx4 v[230:231], off
	s_waitcnt vmcnt(6)
	s_waitcnt lgkmcnt(0)
	s_barrier
	s_setprio 1
	v_mfma_f32_16x16x32_bf16 v[30:33], v[98:101], v[198:201], v[30:33]
	v_mfma_f32_16x16x32_bf16 v[26:29], v[106:109], v[198:201], v[26:29]
	v_mfma_f32_16x16x32_bf16 v[22:25], v[98:101], v[206:209], v[22:25]
	v_mfma_f32_16x16x32_bf16 v[18:21], v[106:109], v[206:209], v[18:21]
	v_lshl_add_u64 v[230:231], v[234:235], 0, s[38:39]
	s_mov_b32 m0, s62
	s_nop 0
	global_load_lds_dwordx4 v[230:231], off
	v_mfma_f32_16x16x32_bf16 v[14:17], v[98:101], v[214:217], v[14:17]
	v_mfma_f32_16x16x32_bf16 v[10:13], v[106:109], v[214:217], v[10:13]
	v_mfma_f32_16x16x32_bf16 v[6:9], v[98:101], v[222:225], v[6:9]
	v_mfma_f32_16x16x32_bf16 v[2:5], v[106:109], v[222:225], v[2:5]
	v_mfma_f32_16x16x32_bf16 v[30:33], v[102:105], v[202:205], v[30:33]
	v_mfma_f32_16x16x32_bf16 v[26:29], v[110:113], v[202:205], v[26:29]
	v_mfma_f32_16x16x32_bf16 v[22:25], v[102:105], v[210:213], v[22:25]
	v_mfma_f32_16x16x32_bf16 v[18:21], v[110:113], v[210:213], v[18:21]
	v_lshl_add_u64 v[230:231], v[236:237], 0, s[38:39]
	s_mov_b32 m0, s63
	s_nop 0
	global_load_lds_dwordx4 v[230:231], off
	v_mfma_f32_16x16x32_bf16 v[14:17], v[102:105], v[218:221], v[14:17]
	v_mfma_f32_16x16x32_bf16 v[10:13], v[110:113], v[218:221], v[10:13]
	v_mfma_f32_16x16x32_bf16 v[6:9], v[102:105], v[226:229], v[6:9]
	v_mfma_f32_16x16x32_bf16 v[2:5], v[110:113], v[226:229], v[2:5]
	v_mfma_f32_16x16x32_bf16 v[82:85], v[146:149], v[198:201], v[82:85]
	v_mfma_f32_16x16x32_bf16 v[110:113], v[150:153], v[202:205], v[82:85]
	v_mfma_f32_16x16x32_bf16 v[82:85], v[180:183], v[198:201], v[86:89]
	v_mfma_f32_16x16x32_bf16 v[106:109], v[194:197], v[202:205], v[82:85]
	v_mfma_f32_16x16x32_bf16 v[82:85], v[146:149], v[206:209], v[90:93]
	v_mfma_f32_16x16x32_bf16 v[102:105], v[150:153], v[210:213], v[82:85]
	v_mfma_f32_16x16x32_bf16 v[82:85], v[180:183], v[206:209], v[94:97]
	v_mfma_f32_16x16x32_bf16 v[78:81], v[146:149], v[214:217], v[78:81]
	v_mfma_f32_16x16x32_bf16 v[74:77], v[180:183], v[214:217], v[74:77]
	v_mfma_f32_16x16x32_bf16 v[70:73], v[146:149], v[222:225], v[70:73]
	v_mfma_f32_16x16x32_bf16 v[66:69], v[180:183], v[222:225], v[66:69]
	v_mfma_f32_16x16x32_bf16 v[98:101], v[194:197], v[210:213], v[82:85]
	v_mfma_f32_16x16x32_bf16 v[78:81], v[150:153], v[218:221], v[78:81]
	v_mfma_f32_16x16x32_bf16 v[74:77], v[194:197], v[218:221], v[74:77]
	v_mfma_f32_16x16x32_bf16 v[70:73], v[150:153], v[226:229], v[70:73]
	v_mfma_f32_16x16x32_bf16 v[66:69], v[194:197], v[226:229], v[66:69]
	s_setprio 0
	s_barrier
	s_add_i32 s84, s84, 2
	s_add_u32 s10, s10, 0x100
	s_addc_u32 s11, s11, 0
	s_add_u32 s43, s43, 0x100
	s_addc_u32 s45, s45, 0
	s_cmp_gt_u32 s84, 13
	s_cbranch_scc0 .LBB0_2599
	s_and_b64 vcc, exec, s[40:41]
	s_cbranch_vccz .LBB0_2602
	s_barrier

.LBB0_4727:
	ds_read_b128 v[146:149], v159
	ds_read_b128 v[150:153], v159 offset:1024
	ds_read_b128 v[154:157], v159 offset:2048
	ds_read_b128 v[164:167], v159 offset:3072
	ds_read_b128 v[168:171], v160
	ds_read_b128 v[172:175], v160 offset:1024
	ds_read_b128 v[176:179], v160 offset:2048
	ds_read_b128 v[180:183], v160 offset:3072
	s_add_u32 s20, s18, 0xfff50080
	s_addc_u32 s21, s19, -1
	s_cmp_eq_u32 s51, 40
	s_cselect_b32 s23, s7, s21
	s_cselect_b32 s22, s6, s20
	s_cselect_b32 s21, s9, s50
	s_cselect_b32 s20, s8, s49
	v_lshl_add_u64 v[216:217], s[18:19], 0, v[138:139]
	s_add_i32 m0, s31, 0xc000
	ds_read_b128 v[184:187], v161
	ds_read_b128 v[188:191], v161 offset:1024
	ds_read_b128 v[192:195], v161 offset:2048
	ds_read_b128 v[196:199], v161 offset:3072
	ds_read_b128 v[200:203], v161 offset:4096
	ds_read_b128 v[204:207], v161 offset:5120
	ds_read_b128 v[208:211], v161 offset:6144
	ds_read_b128 v[212:215], v161 offset:7168
	global_load_lds_dwordx4 v[216:217], off
	v_lshl_add_u64 v[216:217], s[18:19], 0, v[140:141]
	s_add_i32 m0, s31, 0xe000
	s_nop 0
	global_load_lds_dwordx4 v[216:217], off
	s_waitcnt vmcnt(8)
	s_waitcnt lgkmcnt(0)
	s_barrier
	s_setprio 1
	v_mfma_f32_16x16x32_bf16 v[126:129], v[146:149], v[184:187], v[126:129]
	v_mfma_f32_16x16x32_bf16 v[122:125], v[154:157], v[184:187], v[122:125]
	v_mfma_f32_16x16x32_bf16 v[118:121], v[146:149], v[192:195], v[118:121]
	v_mfma_f32_16x16x32_bf16 v[114:117], v[154:157], v[192:195], v[114:117]
	v_mfma_f32_16x16x32_bf16 v[106:109], v[146:149], v[200:203], v[106:109]
	v_mfma_f32_16x16x32_bf16 v[98:101], v[154:157], v[200:203], v[98:101]
	v_mfma_f32_16x16x32_bf16 v[90:93], v[146:149], v[208:211], v[90:93]
	v_mfma_f32_16x16x32_bf16 v[82:85], v[154:157], v[208:211], v[82:85]
	v_mfma_f32_16x16x32_bf16 v[126:129], v[150:153], v[188:191], v[126:129]
	v_mfma_f32_16x16x32_bf16 v[122:125], v[164:167], v[188:191], v[122:125]
	v_mfma_f32_16x16x32_bf16 v[118:121], v[150:153], v[196:199], v[118:121]
	v_mfma_f32_16x16x32_bf16 v[114:117], v[164:167], v[196:199], v[114:117]
	v_mfma_f32_16x16x32_bf16 v[106:109], v[150:153], v[204:207], v[106:109]
	v_mfma_f32_16x16x32_bf16 v[98:101], v[164:167], v[204:207], v[98:101]
	v_mfma_f32_16x16x32_bf16 v[90:93], v[150:153], v[212:215], v[90:93]
	v_mfma_f32_16x16x32_bf16 v[82:85], v[164:167], v[212:215], v[82:85]
	v_mfma_f32_16x16x32_bf16 v[110:113], v[168:171], v[184:187], v[110:113]
	v_mfma_f32_16x16x32_bf16 v[102:105], v[176:179], v[184:187], v[102:105]
	v_mfma_f32_16x16x32_bf16 v[94:97], v[168:171], v[192:195], v[94:97]
	v_mfma_f32_16x16x32_bf16 v[86:89], v[176:179], v[192:195], v[86:89]
	v_mfma_f32_16x16x32_bf16 v[78:81], v[168:171], v[200:203], v[78:81]
	v_mfma_f32_16x16x32_bf16 v[74:77], v[176:179], v[200:203], v[74:77]
	v_mfma_f32_16x16x32_bf16 v[70:73], v[168:171], v[208:211], v[70:73]
	v_mfma_f32_16x16x32_bf16 v[66:69], v[176:179], v[208:211], v[66:69]
	v_mfma_f32_16x16x32_bf16 v[110:113], v[172:175], v[188:191], v[110:113]
	v_mfma_f32_16x16x32_bf16 v[102:105], v[180:183], v[188:191], v[102:105]
	v_mfma_f32_16x16x32_bf16 v[94:97], v[172:175], v[196:199], v[94:97]
	v_mfma_f32_16x16x32_bf16 v[86:89], v[180:183], v[196:199], v[86:89]
	v_mfma_f32_16x16x32_bf16 v[78:81], v[172:175], v[204:207], v[78:81]
	v_mfma_f32_16x16x32_bf16 v[74:77], v[180:183], v[204:207], v[74:77]
	v_mfma_f32_16x16x32_bf16 v[70:73], v[172:175], v[212:215], v[70:73]
	v_mfma_f32_16x16x32_bf16 v[66:69], v[180:183], v[212:215], v[66:69]
	s_setprio 0
	s_barrier
	s_add_i32 s52, s41, s30
	v_lshl_add_u64 v[216:217], s[20:21], 0, v[132:133]
	s_mov_b32 m0, s52
	ds_read_b128 v[184:187], v161 offset:16384
	ds_read_b128 v[188:191], v161 offset:17408
	ds_read_b128 v[192:195], v161 offset:18432
	ds_read_b128 v[196:199], v161 offset:19456
	ds_read_b128 v[200:203], v161 offset:20480
	ds_read_b128 v[204:207], v161 offset:21504
	ds_read_b128 v[208:211], v161 offset:22528
	ds_read_b128 v[212:215], v161 offset:23552
	global_load_lds_dwordx4 v[216:217], off
	s_add_i32 m0, s52, 0x2000
	s_add_u32 s52, s20, 0xb0000
	v_lshl_add_u64 v[218:219], s[20:21], 0, v[136:137]
	s_addc_u32 s53, s21, 0
	s_add_i32 s54, s42, s30
	global_load_lds_dwordx4 v[218:219], off
	v_lshl_add_u64 v[220:221], s[52:53], 0, v[132:133]
	s_mov_b32 m0, s54
	v_lshl_add_u64 v[222:223], s[22:23], 0, v[134:135]
	global_load_lds_dwordx4 v[220:221], off
	v_lshl_add_u64 v[220:221], s[52:53], 0, v[136:137]
	s_add_i32 m0, s54, 0x2000
	s_nop 0
	global_load_lds_dwordx4 v[220:221], off
	s_waitcnt vmcnt(6)
	s_waitcnt lgkmcnt(0)
	s_barrier
	s_setprio 1
	v_mfma_f32_16x16x32_bf16 v[62:65], v[146:149], v[184:187], v[62:65]
	v_mfma_f32_16x16x32_bf16 v[58:61], v[154:157], v[184:187], v[58:61]
	v_mfma_f32_16x16x32_bf16 v[54:57], v[146:149], v[192:195], v[54:57]
	v_mfma_f32_16x16x32_bf16 v[46:49], v[154:157], v[192:195], v[46:49]
	v_lshl_add_u64 v[220:221], s[22:23], 0, v[130:131]
	s_mov_b32 m0, s31
	s_nop 0
	global_load_lds_dwordx4 v[220:221], off
	v_mfma_f32_16x16x32_bf16 v[38:41], v[146:149], v[200:203], v[38:41]
	v_mfma_f32_16x16x32_bf16 v[30:33], v[154:157], v[200:203], v[30:33]
	v_mfma_f32_16x16x32_bf16 v[22:25], v[146:149], v[208:211], v[22:25]
	v_mfma_f32_16x16x32_bf16 v[14:17], v[154:157], v[208:211], v[14:17]
	v_mfma_f32_16x16x32_bf16 v[62:65], v[150:153], v[188:191], v[62:65]
	v_mfma_f32_16x16x32_bf16 v[58:61], v[164:167], v[188:191], v[58:61]
	v_mfma_f32_16x16x32_bf16 v[54:57], v[150:153], v[196:199], v[54:57]
	v_mfma_f32_16x16x32_bf16 v[46:49], v[164:167], v[196:199], v[46:49]
	s_mov_b32 m0, s33
	s_nop 0
	global_load_lds_dwordx4 v[222:223], off
	v_mfma_f32_16x16x32_bf16 v[38:41], v[150:153], v[204:207], v[38:41]
	v_mfma_f32_16x16x32_bf16 v[30:33], v[164:167], v[204:207], v[30:33]
	v_mfma_f32_16x16x32_bf16 v[22:25], v[150:153], v[212:215], v[22:25]
	v_mfma_f32_16x16x32_bf16 v[14:17], v[164:167], v[212:215], v[14:17]
	v_mfma_f32_16x16x32_bf16 v[50:53], v[168:171], v[184:187], v[50:53]
	v_mfma_f32_16x16x32_bf16 v[42:45], v[176:179], v[184:187], v[42:45]
	v_mfma_f32_16x16x32_bf16 v[34:37], v[168:171], v[192:195], v[34:37]
	v_mfma_f32_16x16x32_bf16 v[26:29], v[176:179], v[192:195], v[26:29]
	v_mfma_f32_16x16x32_bf16 v[18:21], v[168:171], v[200:203], v[18:21]
	v_mfma_f32_16x16x32_bf16 v[10:13], v[176:179], v[200:203], v[10:13]
	v_mfma_f32_16x16x32_bf16 v[6:9], v[168:171], v[208:211], v[6:9]
	v_mfma_f32_16x16x32_bf16 v[2:5], v[176:179], v[208:211], v[2:5]
	v_mfma_f32_16x16x32_bf16 v[50:53], v[172:175], v[188:191], v[50:53]
	v_mfma_f32_16x16x32_bf16 v[42:45], v[180:183], v[188:191], v[42:45]
	v_mfma_f32_16x16x32_bf16 v[34:37], v[172:175], v[196:199], v[34:37]
	v_mfma_f32_16x16x32_bf16 v[26:29], v[180:183], v[196:199], v[26:29]
	v_mfma_f32_16x16x32_bf16 v[18:21], v[172:175], v[204:207], v[18:21]
	v_mfma_f32_16x16x32_bf16 v[10:13], v[180:183], v[204:207], v[10:13]
	v_mfma_f32_16x16x32_bf16 v[6:9], v[172:175], v[212:215], v[6:9]
	v_mfma_f32_16x16x32_bf16 v[2:5], v[180:183], v[212:215], v[2:5]
	s_setprio 0
	s_barrier
	ds_read_b128 v[146:149], v162
	ds_read_b128 v[150:153], v162 offset:1024
	ds_read_b128 v[154:157], v162 offset:2048
	ds_read_b128 v[164:167], v162 offset:3072
	ds_read_b128 v[168:171], v163
	ds_read_b128 v[172:175], v163 offset:1024
	ds_read_b128 v[176:179], v163 offset:2048
	ds_read_b128 v[180:183], v163 offset:3072
	s_add_u32 s22, s22, 0xb0000
	s_addc_u32 s23, s23, 0
	s_mov_b32 m0, s34
	v_lshl_add_u64 v[224:225], s[22:23], 0, v[130:131]
	ds_read_b128 v[184:187], v161 offset:32768
	ds_read_b128 v[188:191], v161 offset:33792
	ds_read_b128 v[192:195], v161 offset:34816
	ds_read_b128 v[196:199], v161 offset:35840
	ds_read_b128 v[200:203], v161 offset:36864
	ds_read_b128 v[204:207], v161 offset:37888
	ds_read_b128 v[208:211], v161 offset:38912
	ds_read_b128 v[212:215], v161 offset:39936
	global_load_lds_dwordx4 v[224:225], off
	v_lshl_add_u64 v[224:225], s[22:23], 0, v[134:135]
	s_mov_b32 m0, s35
	s_nop 0
	global_load_lds_dwordx4 v[224:225], off
	s_waitcnt vmcnt(8)
	s_waitcnt lgkmcnt(0)
	s_barrier
	s_setprio 1
	v_mfma_f32_16x16x32_bf16 v[126:129], v[146:149], v[184:187], v[126:129]
	v_mfma_f32_16x16x32_bf16 v[122:125], v[154:157], v[184:187], v[122:125]
	v_mfma_f32_16x16x32_bf16 v[118:121], v[146:149], v[192:195], v[118:121]
	v_mfma_f32_16x16x32_bf16 v[114:117], v[154:157], v[192:195], v[114:117]
	v_mfma_f32_16x16x32_bf16 v[106:109], v[146:149], v[200:203], v[106:109]
	v_mfma_f32_16x16x32_bf16 v[98:101], v[154:157], v[200:203], v[98:101]
	v_mfma_f32_16x16x32_bf16 v[90:93], v[146:149], v[208:211], v[90:93]
	v_mfma_f32_16x16x32_bf16 v[82:85], v[154:157], v[208:211], v[82:85]
	v_mfma_f32_16x16x32_bf16 v[126:129], v[150:153], v[188:191], v[126:129]
	v_mfma_f32_16x16x32_bf16 v[122:125], v[164:167], v[188:191], v[122:125]
	v_mfma_f32_16x16x32_bf16 v[118:121], v[150:153], v[196:199], v[118:121]
	v_mfma_f32_16x16x32_bf16 v[114:117], v[164:167], v[196:199], v[114:117]
	v_mfma_f32_16x16x32_bf16 v[106:109], v[150:153], v[204:207], v[106:109]
	v_mfma_f32_16x16x32_bf16 v[98:101], v[164:167], v[204:207], v[98:101]
	v_mfma_f32_16x16x32_bf16 v[90:93], v[150:153], v[212:215], v[90:93]
	v_mfma_f32_16x16x32_bf16 v[82:85], v[164:167], v[212:215], v[82:85]
	v_mfma_f32_16x16x32_bf16 v[110:113], v[168:171], v[184:187], v[110:113]
	v_mfma_f32_16x16x32_bf16 v[102:105], v[176:179], v[184:187], v[102:105]
	v_mfma_f32_16x16x32_bf16 v[94:97], v[168:171], v[192:195], v[94:97]
	v_mfma_f32_16x16x32_bf16 v[86:89], v[176:179], v[192:195], v[86:89]
	v_mfma_f32_16x16x32_bf16 v[78:81], v[168:171], v[200:203], v[78:81]
	v_mfma_f32_16x16x32_bf16 v[74:77], v[176:179], v[200:203], v[74:77]
	v_mfma_f32_16x16x32_bf16 v[70:73], v[168:171], v[208:211], v[70:73]
	v_mfma_f32_16x16x32_bf16 v[66:69], v[176:179], v[208:211], v[66:69]
	v_mfma_f32_16x16x32_bf16 v[110:113], v[172:175], v[188:191], v[110:113]
	v_mfma_f32_16x16x32_bf16 v[102:105], v[180:183], v[188:191], v[102:105]
	v_mfma_f32_16x16x32_bf16 v[94:97], v[172:175], v[196:199], v[94:97]
	v_mfma_f32_16x16x32_bf16 v[86:89], v[180:183], v[196:199], v[86:89]
	v_mfma_f32_16x16x32_bf16 v[78:81], v[172:175], v[204:207], v[78:81]
	v_mfma_f32_16x16x32_bf16 v[74:77], v[180:183], v[204:207], v[74:77]
	v_mfma_f32_16x16x32_bf16 v[70:73], v[172:175], v[212:215], v[70:73]
	v_mfma_f32_16x16x32_bf16 v[66:69], v[180:183], v[212:215], v[66:69]
	s_setprio 0
	s_barrier
	s_add_i32 s22, s43, s30
	v_lshl_add_u64 v[216:217], v[216:217], 0, s[10:11]
	s_mov_b32 m0, s22
	ds_read_b128 v[184:187], v161 offset:49152
	ds_read_b128 v[188:191], v161 offset:50176
	ds_read_b128 v[192:195], v161 offset:51200
	ds_read_b128 v[196:199], v161 offset:52224
	ds_read_b128 v[200:203], v161 offset:53248
	ds_read_b128 v[204:207], v161 offset:54272
	ds_read_b128 v[208:211], v161 offset:55296
	ds_read_b128 v[212:215], v161 offset:56320
	global_load_lds_dwordx4 v[216:217], off
	s_add_i32 m0, s22, 0x2000
	s_add_u32 s20, s20, 0xb0080
	v_lshl_add_u64 v[216:217], v[218:219], 0, s[10:11]
	s_addc_u32 s21, s21, 0
	s_add_i32 s22, s44, s30
	global_load_lds_dwordx4 v[216:217], off
	v_lshl_add_u64 v[216:217], s[20:21], 0, v[132:133]
	s_mov_b32 m0, s22
	s_nop 0
	global_load_lds_dwordx4 v[216:217], off
	v_lshl_add_u64 v[216:217], s[20:21], 0, v[136:137]
	s_add_i32 m0, s22, 0x2000
	s_nop 0
	global_load_lds_dwordx4 v[216:217], off
	s_waitcnt vmcnt(6)
	s_waitcnt lgkmcnt(0)
	s_barrier
	s_setprio 1
	v_mfma_f32_16x16x32_bf16 v[62:65], v[146:149], v[184:187], v[62:65]
	v_mfma_f32_16x16x32_bf16 v[58:61], v[154:157], v[184:187], v[58:61]
	v_mfma_f32_16x16x32_bf16 v[54:57], v[146:149], v[192:195], v[54:57]
	v_mfma_f32_16x16x32_bf16 v[46:49], v[154:157], v[192:195], v[46:49]
	v_lshl_add_u64 v[216:217], v[220:221], 0, s[10:11]
	s_mov_b32 m0, s37
	s_nop 0
	global_load_lds_dwordx4 v[216:217], off
	v_mfma_f32_16x16x32_bf16 v[38:41], v[146:149], v[200:203], v[38:41]
	v_mfma_f32_16x16x32_bf16 v[30:33], v[154:157], v[200:203], v[30:33]
	v_mfma_f32_16x16x32_bf16 v[22:25], v[146:149], v[208:211], v[22:25]
	v_mfma_f32_16x16x32_bf16 v[14:17], v[154:157], v[208:211], v[14:17]
	v_mfma_f32_16x16x32_bf16 v[62:65], v[150:153], v[188:191], v[62:65]
	v_mfma_f32_16x16x32_bf16 v[58:61], v[164:167], v[188:191], v[58:61]
	v_mfma_f32_16x16x32_bf16 v[54:57], v[150:153], v[196:199], v[54:57]
	v_mfma_f32_16x16x32_bf16 v[46:49], v[164:167], v[196:199], v[46:49]
	v_lshl_add_u64 v[216:217], v[222:223], 0, s[10:11]
	s_mov_b32 m0, s38
	s_nop 0
	global_load_lds_dwordx4 v[216:217], off
	v_mfma_f32_16x16x32_bf16 v[38:41], v[150:153], v[204:207], v[38:41]
	v_mfma_f32_16x16x32_bf16 v[30:33], v[164:167], v[204:207], v[30:33]
	v_mfma_f32_16x16x32_bf16 v[22:25], v[150:153], v[212:215], v[22:25]
	v_mfma_f32_16x16x32_bf16 v[14:17], v[164:167], v[212:215], v[14:17]
	v_mfma_f32_16x16x32_bf16 v[50:53], v[168:171], v[184:187], v[50:53]
	v_mfma_f32_16x16x32_bf16 v[42:45], v[176:179], v[184:187], v[42:45]
	v_mfma_f32_16x16x32_bf16 v[34:37], v[168:171], v[192:195], v[34:37]
	v_mfma_f32_16x16x32_bf16 v[26:29], v[176:179], v[192:195], v[26:29]
	v_mfma_f32_16x16x32_bf16 v[18:21], v[168:171], v[200:203], v[18:21]
	v_mfma_f32_16x16x32_bf16 v[10:13], v[176:179], v[200:203], v[10:13]
	v_mfma_f32_16x16x32_bf16 v[6:9], v[168:171], v[208:211], v[6:9]
	v_mfma_f32_16x16x32_bf16 v[2:5], v[176:179], v[208:211], v[2:5]
	v_mfma_f32_16x16x32_bf16 v[50:53], v[172:175], v[188:191], v[50:53]
	v_mfma_f32_16x16x32_bf16 v[42:45], v[180:183], v[188:191], v[42:45]
	v_mfma_f32_16x16x32_bf16 v[34:37], v[172:175], v[196:199], v[34:37]
	v_mfma_f32_16x16x32_bf16 v[26:29], v[180:183], v[196:199], v[26:29]
	v_mfma_f32_16x16x32_bf16 v[18:21], v[172:175], v[204:207], v[18:21]
	v_mfma_f32_16x16x32_bf16 v[10:13], v[180:183], v[204:207], v[10:13]
	v_mfma_f32_16x16x32_bf16 v[6:9], v[172:175], v[212:215], v[6:9]
	v_mfma_f32_16x16x32_bf16 v[2:5], v[180:183], v[212:215], v[2:5]
	s_setprio 0
	s_barrier
	s_add_i32 s51, s51, 2
	s_add_u32 s18, s18, 0x100
	s_addc_u32 s19, s19, 0
	s_add_u32 s49, s49, 0x100
	s_addc_u32 s50, s50, 0
	s_cmp_gt_u32 s51, 41
	s_cbranch_scc0 .LBB0_4727
	v_lshl_or_b32 v146, s48, 8, v158
	v_lshl_add_u32 v156, s47, 8, v1
	v_ashrrev_i32_e32 v147, 31, v146
	v_lshlrev_b64 v[146:147], 2, v[146:147]
	v_ashrrev_i32_e32 v157, 31, v156
	v_lshl_add_u64 v[148:149], s[62:63], 0, v[146:147]
	v_lshlrev_b64 v[150:151], 12, v[156:157]
	v_or_b32_e32 v176, 16, v156
	v_lshl_add_u64 v[172:173], v[148:149], 0, v[150:151]
	v_ashrrev_i32_e32 v177, 31, v176
	global_load_dwordx4 v[152:155], v[172:173], off offset:16 nt
	global_load_dwordx4 v[164:167], v[172:173], off nt
	global_load_dwordx4 v[168:171], v[172:173], off offset:528 nt
	s_nop 0
	global_load_dwordx4 v[172:175], v[172:173], off offset:512 nt
	v_lshlrev_b64 v[224:225], 12, v[176:177]
	v_or_b32_e32 v192, 32, v156
	v_lshl_add_u64 v[188:189], v[148:149], 0, v[224:225]
	v_ashrrev_i32_e32 v193, 31, v192
	global_load_dwordx4 v[176:179], v[188:189], off offset:16 nt
	global_load_dwordx4 v[180:183], v[188:189], off nt
	global_load_dwordx4 v[184:187], v[188:189], off offset:528 nt
	s_nop 0
	global_load_dwordx4 v[188:191], v[188:189], off offset:512 nt
	v_lshlrev_b64 v[226:227], 12, v[192:193]
	v_or_b32_e32 v156, 48, v156
	v_lshl_add_u64 v[204:205], v[148:149], 0, v[226:227]
	v_ashrrev_i32_e32 v157, 31, v156
	global_load_dwordx4 v[192:195], v[204:205], off offset:16 nt
	global_load_dwordx4 v[196:199], v[204:205], off nt
	global_load_dwordx4 v[200:203], v[204:205], off offset:528 nt
	s_nop 0
	global_load_dwordx4 v[204:207], v[204:205], off offset:512 nt
	v_lshlrev_b64 v[156:157], 12, v[156:157]
	v_lshl_add_u64 v[220:221], v[148:149], 0, v[156:157]
	global_load_dwordx4 v[208:211], v[220:221], off offset:16 nt
	global_load_dwordx4 v[212:215], v[220:221], off nt
	global_load_dwordx4 v[216:219], v[220:221], off offset:528 nt
	s_nop 0
	global_load_dwordx4 v[220:223], v[220:221], off offset:512 nt
	s_and_b64 vcc, exec, s[4:5]
	s_mov_b32 s48, s45
	s_mov_b32 s47, s46
	s_mov_b64 s[20:21], s[8:9]
	s_mov_b64 s[18:19], s[6:7]
	s_waitcnt vmcnt(0)
	v_pk_fma_f32 v[122:123], v[122:123], 0.5, v[152:153] op_sel_hi:[1,0,1]
	v_lshl_add_u64 v[152:153], s[62:63], 0, v[150:151]
	v_pk_fma_f32 v[128:129], v[128:129], 0.5, v[166:167] op_sel_hi:[1,0,1]
	v_pk_fma_f32 v[126:127], v[126:127], 0.5, v[164:165] op_sel_hi:[1,0,1]
	v_lshl_add_u64 v[152:153], v[152:153], 0, v[146:147]
	v_pk_fma_f32 v[112:113], v[112:113], 0.5, v[174:175] op_sel_hi:[1,0,1]
	v_pk_fma_f32 v[110:111], v[110:111], 0.5, v[172:173] op_sel_hi:[1,0,1]
	v_pk_fma_f32 v[124:125], v[124:125], 0.5, v[154:155] op_sel_hi:[1,0,1]
	global_store_dwordx4 v[152:153], v[126:129], off nt
	global_store_dwordx4 v[152:153], v[122:125], off offset:16 nt
	v_pk_fma_f32 v[104:105], v[104:105], 0.5, v[170:171] op_sel_hi:[1,0,1]
	v_pk_fma_f32 v[102:103], v[102:103], 0.5, v[168:169] op_sel_hi:[1,0,1]
	global_store_dwordx4 v[152:153], v[110:113], off offset:512 nt
	global_store_dwordx4 v[152:153], v[102:105], off offset:528 nt
	v_pk_fma_f32 v[96:97], v[96:97], 0.5, v[190:191] op_sel_hi:[1,0,1]
	v_pk_fma_f32 v[110:111], v[114:115], 0.5, v[176:177] op_sel_hi:[1,0,1]
	v_lshl_add_u64 v[114:115], s[62:63], 0, v[224:225]
	v_pk_fma_f32 v[104:105], v[120:121], 0.5, v[182:183] op_sel_hi:[1,0,1]
	v_pk_fma_f32 v[102:103], v[118:119], 0.5, v[180:181] op_sel_hi:[1,0,1]
	v_lshl_add_u64 v[114:115], v[114:115], 0, v[146:147]
	v_pk_fma_f32 v[94:95], v[94:95], 0.5, v[188:189] op_sel_hi:[1,0,1]
	v_pk_fma_f32 v[112:113], v[116:117], 0.5, v[178:179] op_sel_hi:[1,0,1]
	global_store_dwordx4 v[114:115], v[102:105], off nt
	global_store_dwordx4 v[114:115], v[110:113], off offset:16 nt
	v_pk_fma_f32 v[88:89], v[88:89], 0.5, v[186:187] op_sel_hi:[1,0,1]
	v_pk_fma_f32 v[86:87], v[86:87], 0.5, v[184:185] op_sel_hi:[1,0,1]
	global_store_dwordx4 v[114:115], v[94:97], off offset:512 nt
	global_store_dwordx4 v[114:115], v[86:89], off offset:528 nt
	v_pk_fma_f32 v[80:81], v[80:81], 0.5, v[206:207] op_sel_hi:[1,0,1]
	v_pk_fma_f32 v[94:95], v[98:99], 0.5, v[192:193] op_sel_hi:[1,0,1]
	v_lshl_add_u64 v[98:99], s[62:63], 0, v[226:227]
	v_pk_fma_f32 v[88:89], v[108:109], 0.5, v[198:199] op_sel_hi:[1,0,1]
	v_pk_fma_f32 v[86:87], v[106:107], 0.5, v[196:197] op_sel_hi:[1,0,1]
	v_lshl_add_u64 v[98:99], v[98:99], 0, v[146:147]
	v_pk_fma_f32 v[78:79], v[78:79], 0.5, v[204:205] op_sel_hi:[1,0,1]
	v_pk_fma_f32 v[96:97], v[100:101], 0.5, v[194:195] op_sel_hi:[1,0,1]
	global_store_dwordx4 v[98:99], v[86:89], off nt
	global_store_dwordx4 v[98:99], v[94:97], off offset:16 nt
	v_pk_fma_f32 v[76:77], v[76:77], 0.5, v[202:203] op_sel_hi:[1,0,1]
	v_pk_fma_f32 v[74:75], v[74:75], 0.5, v[200:201] op_sel_hi:[1,0,1]
	global_store_dwordx4 v[98:99], v[78:81], off offset:512 nt
	global_store_dwordx4 v[98:99], v[74:77], off offset:528 nt
	v_pk_fma_f32 v[72:73], v[72:73], 0.5, v[222:223] op_sel_hi:[1,0,1]
	v_pk_fma_f32 v[78:79], v[82:83], 0.5, v[208:209] op_sel_hi:[1,0,1]
	v_lshl_add_u64 v[82:83], s[62:63], 0, v[156:157]
	v_pk_fma_f32 v[76:77], v[92:93], 0.5, v[214:215] op_sel_hi:[1,0,1]
	v_pk_fma_f32 v[74:75], v[90:91], 0.5, v[212:213] op_sel_hi:[1,0,1]
	v_lshl_add_u64 v[82:83], v[82:83], 0, v[146:147]
	v_pk_fma_f32 v[70:71], v[70:71], 0.5, v[220:221] op_sel_hi:[1,0,1]
	v_pk_fma_f32 v[66:67], v[66:67], 0.5, v[216:217] op_sel_hi:[1,0,1]
	v_lshl_add_u64 v[156:157], v[150:151], 0, s[12:13]
	v_pk_fma_f32 v[80:81], v[84:85], 0.5, v[210:211] op_sel_hi:[1,0,1]
	global_store_dwordx4 v[82:83], v[74:77], off nt
	global_store_dwordx4 v[82:83], v[78:81], off offset:16 nt
	v_pk_fma_f32 v[68:69], v[68:69], 0.5, v[218:219] op_sel_hi:[1,0,1]
	global_store_dwordx4 v[82:83], v[70:73], off offset:512 nt
	global_store_dwordx4 v[82:83], v[66:69], off offset:528 nt
	v_lshl_add_u64 v[154:155], v[150:151], 0, s[14:15]
	v_lshl_add_u64 v[152:153], v[150:151], 0, s[16:17]
	v_lshl_add_u64 v[66:67], v[148:149], 0, v[156:157]
	global_load_dwordx4 v[110:113], v[66:67], off offset:16 nt
	global_load_dwordx4 v[122:125], v[66:67], off nt
	global_load_dwordx4 v[94:97], v[66:67], off offset:528 nt
	global_load_dwordx4 v[102:105], v[66:67], off offset:512 nt
	v_lshl_add_u64 v[66:67], v[148:149], 0, v[154:155]
	global_load_dwordx4 v[90:93], v[66:67], off offset:16 nt
	global_load_dwordx4 v[98:101], v[66:67], off nt
	global_load_dwordx4 v[78:81], v[66:67], off offset:528 nt
	global_load_dwordx4 v[86:89], v[66:67], off offset:512 nt
	v_lshl_add_u64 v[70:71], v[148:149], 0, v[152:153]
	global_load_dwordx4 v[74:77], v[70:71], off offset:16 nt
	global_load_dwordx4 v[82:85], v[70:71], off nt
	global_load_dwordx4 v[66:69], v[70:71], off offset:528 nt
	s_nop 0
	global_load_dwordx4 v[70:73], v[70:71], off offset:512 nt
	v_lshl_add_u64 v[150:151], v[150:151], 0, s[2:3]
	v_lshl_add_u64 v[114:115], v[148:149], 0, v[150:151]
	global_load_dwordx4 v[118:121], v[114:115], off offset:16 nt
	global_load_dwordx4 v[126:129], v[114:115], off nt
	global_load_dwordx4 v[106:109], v[114:115], off offset:528 nt
	s_nop 0
	global_load_dwordx4 v[114:117], v[114:115], off offset:512 nt
	s_waitcnt vmcnt(15)
	v_pk_fma_f32 v[58:59], v[58:59], 0.5, v[110:111] op_sel_hi:[1,0,1]
	v_lshl_add_u64 v[110:111], s[62:63], 0, v[156:157]
	s_waitcnt vmcnt(14)
	v_pk_fma_f32 v[64:65], v[64:65], 0.5, v[124:125] op_sel_hi:[1,0,1]
	v_pk_fma_f32 v[62:63], v[62:63], 0.5, v[122:123] op_sel_hi:[1,0,1]
	v_lshl_add_u64 v[110:111], v[110:111], 0, v[146:147]
	s_waitcnt vmcnt(12)
	v_pk_fma_f32 v[52:53], v[52:53], 0.5, v[104:105] op_sel_hi:[1,0,1]
	v_pk_fma_f32 v[50:51], v[50:51], 0.5, v[102:103] op_sel_hi:[1,0,1]
	v_pk_fma_f32 v[60:61], v[60:61], 0.5, v[112:113] op_sel_hi:[1,0,1]
	global_store_dwordx4 v[110:111], v[62:65], off nt
	global_store_dwordx4 v[110:111], v[58:61], off offset:16 nt
	v_pk_fma_f32 v[44:45], v[44:45], 0.5, v[96:97] op_sel_hi:[1,0,1]
	v_pk_fma_f32 v[42:43], v[42:43], 0.5, v[94:95] op_sel_hi:[1,0,1]
	global_store_dwordx4 v[110:111], v[50:53], off offset:512 nt
	global_store_dwordx4 v[110:111], v[42:45], off offset:528 nt
	s_waitcnt vmcnt(12)
	v_pk_fma_f32 v[36:37], v[36:37], 0.5, v[88:89] op_sel_hi:[1,0,1]
	v_lshl_add_u64 v[50:51], s[62:63], 0, v[154:155]
	v_pk_fma_f32 v[44:45], v[56:57], 0.5, v[100:101] op_sel_hi:[1,0,1]
	v_pk_fma_f32 v[42:43], v[54:55], 0.5, v[98:99] op_sel_hi:[1,0,1]
	v_lshl_add_u64 v[50:51], v[50:51], 0, v[146:147]
	v_pk_fma_f32 v[34:35], v[34:35], 0.5, v[86:87] op_sel_hi:[1,0,1]
	v_pk_fma_f32 v[48:49], v[48:49], 0.5, v[92:93] op_sel_hi:[1,0,1]
	v_pk_fma_f32 v[46:47], v[46:47], 0.5, v[90:91] op_sel_hi:[1,0,1]
	global_store_dwordx4 v[50:51], v[42:45], off nt
	global_store_dwordx4 v[50:51], v[46:49], off offset:16 nt
	v_pk_fma_f32 v[28:29], v[28:29], 0.5, v[80:81] op_sel_hi:[1,0,1]
	v_pk_fma_f32 v[26:27], v[26:27], 0.5, v[78:79] op_sel_hi:[1,0,1]
	global_store_dwordx4 v[50:51], v[34:37], off offset:512 nt
	global_store_dwordx4 v[50:51], v[26:29], off offset:528 nt
	s_waitcnt vmcnt(12)
	v_pk_fma_f32 v[20:21], v[20:21], 0.5, v[72:73] op_sel_hi:[1,0,1]
	v_lshl_add_u64 v[34:35], s[62:63], 0, v[152:153]
	v_pk_fma_f32 v[28:29], v[40:41], 0.5, v[84:85] op_sel_hi:[1,0,1]
	v_pk_fma_f32 v[26:27], v[38:39], 0.5, v[82:83] op_sel_hi:[1,0,1]
	v_lshl_add_u64 v[34:35], v[34:35], 0, v[146:147]
	v_pk_fma_f32 v[18:19], v[18:19], 0.5, v[70:71] op_sel_hi:[1,0,1]
	v_pk_fma_f32 v[32:33], v[32:33], 0.5, v[76:77] op_sel_hi:[1,0,1]
	v_pk_fma_f32 v[30:31], v[30:31], 0.5, v[74:75] op_sel_hi:[1,0,1]
	global_store_dwordx4 v[34:35], v[26:29], off nt
	global_store_dwordx4 v[34:35], v[30:33], off offset:16 nt
	v_pk_fma_f32 v[12:13], v[12:13], 0.5, v[68:69] op_sel_hi:[1,0,1]
	v_pk_fma_f32 v[10:11], v[10:11], 0.5, v[66:67] op_sel_hi:[1,0,1]
	global_store_dwordx4 v[34:35], v[18:21], off offset:512 nt
	global_store_dwordx4 v[34:35], v[10:13], off offset:528 nt
	s_waitcnt vmcnt(12)
	v_pk_fma_f32 v[8:9], v[8:9], 0.5, v[116:117] op_sel_hi:[1,0,1]
	v_lshl_add_u64 v[18:19], s[62:63], 0, v[150:151]
	v_pk_fma_f32 v[12:13], v[24:25], 0.5, v[128:129] op_sel_hi:[1,0,1]
	v_pk_fma_f32 v[10:11], v[22:23], 0.5, v[126:127] op_sel_hi:[1,0,1]
	v_lshl_add_u64 v[18:19], v[18:19], 0, v[146:147]
	v_pk_fma_f32 v[6:7], v[6:7], 0.5, v[114:115] op_sel_hi:[1,0,1]
	v_pk_fma_f32 v[16:17], v[16:17], 0.5, v[120:121] op_sel_hi:[1,0,1]
	v_pk_fma_f32 v[14:15], v[14:15], 0.5, v[118:119] op_sel_hi:[1,0,1]
	global_store_dwordx4 v[18:19], v[10:13], off nt
	global_store_dwordx4 v[18:19], v[14:17], off offset:16 nt
	v_pk_fma_f32 v[4:5], v[4:5], 0.5, v[108:109] op_sel_hi:[1,0,1]
	v_pk_fma_f32 v[2:3], v[2:3], 0.5, v[106:107] op_sel_hi:[1,0,1]
	global_store_dwordx4 v[18:19], v[6:9], off offset:512 nt
	global_store_dwordx4 v[18:19], v[2:5], off offset:528 nt
	s_cbranch_vccz .LBB0_4716
	s_waitcnt vmcnt(0)
	s_cmpk_gt_u32 s24, 0xff
	s_cbranch_scc1 .LBB0_4731
	s_barrier
